# accumulator clearing removed: peeled first K-loop pass takes C=0 (5 of 7 GEMM phases)
# speedup vs baseline: 1.0101x; 1.0101x over previous
; #define PG8_STAGE(bufoff, gbase, voff) do { _Pragma("unroll") for (int _i = 0; _i < 2; ++_i) \
;         __builtin_amdgcn_global_load_lds((const unsigned*)((const char*)(gbase) + (voff)[_i]), (PG8_LAS unsigned*)(lds + (bufoff) + ldsw + _i * 8192), 16, 0, 0); } while (0)
; #define PG8_LDA(dst, b, h) do { _Pragma("unroll") for (int m = 0; m < 4; ++m) _Pragma("unroll") for (int k = 0; k < 2; ++k) dst[m][k] = *(const PG8_LAS bf16x8*)(lds + PG8_SA(b, h) + aoff + m * 2048 + k * 1024); } while (0)
; #define PG8_LDB(dst, b, h) do { _Pragma("unroll") for (int n = 0; n < 2; ++n) _Pragma("unroll") for (int k = 0; k < 2; ++k) dst[n][k] = *(const PG8_LAS bf16x8*)(lds + PG8_SB(b, h) + boff + n * 2048 + k * 1024); } while (0)
; #define PG8_MMA_NP(ai, bj, At, Bt) do { _Pragma("unroll") for (int m = 0; m < 4; ++m) _Pragma("unroll") for (int n = 0; n < 2; ++n) _Pragma("unroll") for (int k = 0; k < 2; ++k) \
;         acc[ai][bj][m][n] = __builtin_amdgcn_mfma_f32_16x16x32_bf16(Bt[n][k], At[m][k], acc[ai][bj][m][n], 0, 0, 0); } while (0)
; #define PG8_WAIT_V(n) asm volatile("s_waitcnt vmcnt(" #n ")" ::: "memory")
; #define PG8_BAR __builtin_amdgcn_s_barrier()
; template <class Epi, class Sched, bool ALIGN_EPI = false, bool SP2 = false>
; __device__ __forceinline__ void gemm_phase(PG8_LAS unsigned char* lds, const Gemm g, const Sched& S, const Epi& E) {
;     ...
;     Unit cur, nxt; int ui = 0;
;     if (!S.next(0, cur)) return;
;     f32x4 acc[2][2][4][2];
; #pragma unroll
;     for (int a = 0; a < 2; ++a)
; #pragma unroll
;         for (int b = 0; b < 2; ++b)
; #pragma unroll
;             for (int m = 0; m < 4; ++m)
; #pragma unroll
;                 for (int n = 0; n < 2; ++n) acc[a][b][m][n] = (f32x4){0.f, 0.f, 0.f, 0.f};
;     ...
;             PG8_LDB(B0, 0, 0); PG8_LDB(B1, 0, 1); PG8_SCHED; PG8_LDA(At, 0, 0); PG8_STAGE(PG8_SA(1, 1), a1 + hstep, voffA);
;             PG8_WAIT_V(8); PG8_WAIT_L(0); PG8_BAR; __builtin_amdgcn_s_setprio(1); PG8_MMA_NP(0, 0, At, B0); PG8_MMA_NP(0, 1, At, B1); __builtin_amdgcn_s_setprio(0); PG8_BAR; PG8_SCHED;
;             PG8_LDA(At, 0, 1); PG8_STAGE(PG8_SB(0, 0), b2, voffB); PG8_STAGE(PG8_SB(0, 1), b2 + hstep, voffB); PG8_STAGE(PG8_SA(0, 0), a2, voffA);
;             PG8_WAIT_V(8); PG8_WAIT_L(0); PG8_BAR; __builtin_amdgcn_s_setprio(1); PG8_MMA_NP(1, 0, At, B0); PG8_MMA_NP(1, 1, At, B1); __builtin_amdgcn_s_setprio(0); PG8_BAR; PG8_SCHED;
.LBB0_165:
	s_ashr_i32 s47, s46, 31
	s_lshl_b64 s[14:15], s[46:47], 19
	s_add_u32 s50, s86, s14
	s_addc_u32 s51, s87, s15
	s_and_b64 s[14:15], s[40:41], exec
	s_cselect_b32 s47, s51, s3
	s_cselect_b32 s59, s50, s2
	s_ashr_i32 s45, s44, 31
	s_lshl_b64 s[14:15], s[44:45], 19
	v_readlane_b32 s22, v244, 18
	s_add_u32 s52, s22, s14
	v_readlane_b32 s14, v244, 19
	s_addc_u32 s53, s14, s15
	s_and_b64 s[14:15], s[40:41], exec
	s_cselect_b32 s45, s53, s13
	s_cselect_b32 s60, s52, s12
	s_add_u32 s2, s2, 0x40080
	s_addc_u32 s3, s3, 0
	s_add_u32 s61, s12, 0x100
	s_addc_u32 s62, s13, 0
	s_mov_b32 s63, -2
	s_add_u32 s12, s2, 0xfffc0080
	s_addc_u32 s13, s3, -1
	s_add_i32 s22, 0, 0x10000
	s_cmp_eq_u32 s63, 12
	s_cselect_b32 s15, s47, s13
	s_cselect_b32 s14, s59, s12
	s_cselect_b32 s13, s45, s62
	s_cselect_b32 s12, s60, s61
	s_add_i32 s23, 0, 0x14000
	v_add_u32_e32 v154, s22, v183
	v_add_u32_e32 v162, s23, v183
	ds_read_b128 v[130:133], v154
	ds_read_b128 v[146:149], v154 offset:1024
	ds_read_b128 v[150:153], v154 offset:2048
	ds_read_b128 v[154:157], v154 offset:3072
	ds_read_b128 v[158:161], v162
	ds_read_b128 v[178:181], v162 offset:1024
	ds_read_b128 v[186:189], v162 offset:2048
	ds_read_b128 v[202:205], v162 offset:3072
	v_lshl_add_u64 v[162:163], s[2:3], 0, v[142:143]
	s_add_i32 m0, s10, 0xc000
	ds_read_b128 v[206:209], v185
	ds_read_b128 v[210:213], v185 offset:1024
	ds_read_b128 v[214:217], v185 offset:2048
	ds_read_b128 v[218:221], v185 offset:3072
	ds_read_b128 v[222:225], v185 offset:4096
	ds_read_b128 v[226:229], v185 offset:5120
	ds_read_b128 v[230:233], v185 offset:6144
	ds_read_b128 v[234:237], v185 offset:7168
	global_load_lds_dwordx4 v[162:163], off
	v_lshl_add_u64 v[162:163], s[2:3], 0, v[144:145]
	s_add_i32 m0, s10, 0xe000
	s_nop 0
	global_load_lds_dwordx4 v[162:163], off
	s_waitcnt vmcnt(8)
	s_waitcnt lgkmcnt(0)
	s_barrier
	s_setprio 1
	s_waitcnt lgkmcnt(0)
	v_mfma_f32_16x16x32_bf16 v[126:129], v[130:133], v[206:209], 0
	v_mfma_f32_16x16x32_bf16 v[118:121], v[150:153], v[206:209], 0
	v_mfma_f32_16x16x32_bf16 v[110:113], v[130:133], v[214:217], 0
	v_mfma_f32_16x16x32_bf16 v[102:105], v[150:153], v[214:217], 0
	v_mfma_f32_16x16x32_bf16 v[94:97], v[130:133], v[222:225], 0
	v_mfma_f32_16x16x32_bf16 v[86:89], v[150:153], v[222:225], 0
	v_mfma_f32_16x16x32_bf16 v[78:81], v[130:133], v[230:233], 0
	v_mfma_f32_16x16x32_bf16 v[70:73], v[150:153], v[230:233], 0
	v_mfma_f32_16x16x32_bf16 v[122:125], v[158:161], v[206:209], 0
	v_mfma_f32_16x16x32_bf16 v[114:117], v[186:189], v[206:209], 0
	v_mfma_f32_16x16x32_bf16 v[106:109], v[158:161], v[214:217], 0
	v_mfma_f32_16x16x32_bf16 v[98:101], v[186:189], v[214:217], 0
	v_mfma_f32_16x16x32_bf16 v[90:93], v[158:161], v[222:225], 0
	v_mfma_f32_16x16x32_bf16 v[82:85], v[186:189], v[222:225], 0
	v_mfma_f32_16x16x32_bf16 v[74:77], v[158:161], v[230:233], 0
	v_mfma_f32_16x16x32_bf16 v[66:69], v[186:189], v[230:233], 0
	v_mfma_f32_16x16x32_bf16 v[126:129], v[146:149], v[210:213], v[126:129]
	v_mfma_f32_16x16x32_bf16 v[118:121], v[154:157], v[210:213], v[118:121]
	v_mfma_f32_16x16x32_bf16 v[110:113], v[146:149], v[218:221], v[110:113]
	v_mfma_f32_16x16x32_bf16 v[102:105], v[154:157], v[218:221], v[102:105]
	v_mfma_f32_16x16x32_bf16 v[94:97], v[146:149], v[226:229], v[94:97]
	v_mfma_f32_16x16x32_bf16 v[86:89], v[154:157], v[226:229], v[86:89]
	v_mfma_f32_16x16x32_bf16 v[78:81], v[146:149], v[234:237], v[78:81]
	v_mfma_f32_16x16x32_bf16 v[70:73], v[154:157], v[234:237], v[70:73]
	v_mfma_f32_16x16x32_bf16 v[122:125], v[178:181], v[210:213], v[122:125]
	v_mfma_f32_16x16x32_bf16 v[114:117], v[202:205], v[210:213], v[114:117]
	v_mfma_f32_16x16x32_bf16 v[106:109], v[178:181], v[218:221], v[106:109]
	v_mfma_f32_16x16x32_bf16 v[98:101], v[202:205], v[218:221], v[98:101]
	v_mfma_f32_16x16x32_bf16 v[90:93], v[178:181], v[226:229], v[90:93]
	v_mfma_f32_16x16x32_bf16 v[82:85], v[202:205], v[226:229], v[82:85]
	v_mfma_f32_16x16x32_bf16 v[74:77], v[178:181], v[234:237], v[74:77]
	v_mfma_f32_16x16x32_bf16 v[66:69], v[202:205], v[234:237], v[66:69]
	s_setprio 0
	s_barrier
	s_add_i32 s22, s22, s8
	v_lshl_add_u64 v[162:163], s[12:13], 0, v[0:1]
	s_mov_b32 m0, s22
	ds_read_b128 v[206:209], v185 offset:16384
	ds_read_b128 v[210:213], v185 offset:17408
	ds_read_b128 v[214:217], v185 offset:18432
	ds_read_b128 v[218:221], v185 offset:19456
	ds_read_b128 v[222:225], v185 offset:20480
	ds_read_b128 v[226:229], v185 offset:21504
	ds_read_b128 v[230:233], v185 offset:22528
	ds_read_b128 v[234:237], v185 offset:23552
	global_load_lds_dwordx4 v[162:163], off
	s_add_i32 m0, s22, 0x2000
	s_add_u32 s64, s12, 0x40000
	v_lshl_add_u64 v[190:191], s[12:13], 0, v[134:135]
	s_addc_u32 s65, s13, 0
	s_add_i32 s22, s23, s8
	global_load_lds_dwordx4 v[190:191], off
	v_lshl_add_u64 v[238:239], s[64:65], 0, v[0:1]
	s_mov_b32 m0, s22
	v_lshl_add_u64 v[240:241], s[14:15], 0, v[136:137]
	global_load_lds_dwordx4 v[238:239], off
	v_lshl_add_u64 v[238:239], s[64:65], 0, v[134:135]
	s_add_i32 m0, s22, 0x2000
	s_nop 0
	global_load_lds_dwordx4 v[238:239], off
	v_lshl_add_u64 v[238:239], s[14:15], 0, v[138:139]
	s_mov_b32 m0, s10
	s_nop 0
	global_load_lds_dwordx4 v[238:239], off
	s_mov_b32 m0, s29
	s_nop 0
	global_load_lds_dwordx4 v[240:241], off
	s_waitcnt vmcnt(8)
	s_waitcnt lgkmcnt(0)
	s_barrier
; #define PG8_STAGE(bufoff, gbase, voff) do { _Pragma("unroll") for (int _i = 0; _i < 2; ++_i) \
;         __builtin_amdgcn_global_load_lds((const unsigned*)((const char*)(gbase) + (voff)[_i]), (PG8_LAS unsigned*)(lds + (bufoff) + ldsw + _i * 8192), 16, 0, 0); } while (0)
; #define PG8_LDA(dst, b, h) do { _Pragma("unroll") for (int m = 0; m < 4; ++m) _Pragma("unroll") for (int k = 0; k < 2; ++k) dst[m][k] = *(const PG8_LAS bf16x8*)(lds + PG8_SA(b, h) + aoff + m * 2048 + k * 1024); } while (0)
; #define PG8_LDB(dst, b, h) do { _Pragma("unroll") for (int n = 0; n < 2; ++n) _Pragma("unroll") for (int k = 0; k < 2; ++k) dst[n][k] = *(const PG8_LAS bf16x8*)(lds + PG8_SB(b, h) + boff + n * 2048 + k * 1024); } while (0)
; #define PG8_MMA_NP(ai, bj, At, Bt) do { _Pragma("unroll") for (int m = 0; m < 4; ++m) _Pragma("unroll") for (int n = 0; n < 2; ++n) _Pragma("unroll") for (int k = 0; k < 2; ++k) \
;         acc[ai][bj][m][n] = __builtin_amdgcn_mfma_f32_16x16x32_bf16(Bt[n][k], At[m][k], acc[ai][bj][m][n], 0, 0, 0); } while (0)
; #define PG8_WAIT_V(n) asm volatile("s_waitcnt vmcnt(" #n ")" ::: "memory")
; #define PG8_WAIT_L(n) asm volatile("s_waitcnt lgkmcnt(" #n ")" ::: "memory")
; #define PG8_BAR __builtin_amdgcn_s_barrier()
; #define PG8_SCHED __builtin_amdgcn_sched_barrier(0)
; template <class Epi, class Sched, bool ALIGN_EPI = false, bool SP2 = false>
; __device__ __forceinline__ void gemm_phase(PG8_LAS unsigned char* lds, const Gemm g, const Sched& S, const Epi& E) {
;     ...
;             PG8_WAIT_V(8); PG8_WAIT_L(0); PG8_BAR; __builtin_amdgcn_s_setprio(1); PG8_MMA_NP(0, 0, At, B0); PG8_MMA_NP(0, 1, At, B1); __builtin_amdgcn_s_setprio(0); PG8_BAR; PG8_SCHED;
;             PG8_LDA(At, 0, 1); PG8_STAGE(PG8_SB(0, 0), b2, voffB); PG8_STAGE(PG8_SB(0, 1), b2 + hstep, voffB); PG8_STAGE(PG8_SA(0, 0), a2, voffA);
;             PG8_WAIT_V(8); PG8_WAIT_L(0); PG8_BAR; __builtin_amdgcn_s_setprio(1); PG8_MMA_NP(1, 0, At, B0); PG8_MMA_NP(1, 1, At, B1); __builtin_amdgcn_s_setprio(0); PG8_BAR; PG8_SCHED;
;             PG8_LDB(B0, 1, 0); PG8_LDB(B1, 1, 1); PG8_SCHED; PG8_LDA(At, 1, 0); PG8_STAGE(PG8_SA(0, 1), a2 + hstep, voffA);
;             PG8_WAIT_V(8); PG8_WAIT_L(0); PG8_BAR; __builtin_amdgcn_s_setprio(1); PG8_MMA_NP(0, 0, At, B0); PG8_MMA_NP(0, 1, At, B1); __builtin_amdgcn_s_setprio(0); PG8_BAR; PG8_SCHED;
	s_setprio 1
	s_waitcnt lgkmcnt(0)
	v_mfma_f32_16x16x32_bf16 v[62:65], v[130:133], v[206:209], 0
	v_mfma_f32_16x16x32_bf16 v[54:57], v[150:153], v[206:209], 0
	v_mfma_f32_16x16x32_bf16 v[46:49], v[130:133], v[214:217], 0
	v_mfma_f32_16x16x32_bf16 v[38:41], v[150:153], v[214:217], 0
	v_mfma_f32_16x16x32_bf16 v[30:33], v[130:133], v[222:225], 0
	v_mfma_f32_16x16x32_bf16 v[22:25], v[150:153], v[222:225], 0
	v_mfma_f32_16x16x32_bf16 v[14:17], v[130:133], v[230:233], 0
	v_mfma_f32_16x16x32_bf16 v[6:9], v[150:153], v[230:233], 0
	v_mfma_f32_16x16x32_bf16 v[58:61], v[158:161], v[206:209], 0
	v_mfma_f32_16x16x32_bf16 v[50:53], v[186:189], v[206:209], 0
	v_mfma_f32_16x16x32_bf16 v[42:45], v[158:161], v[214:217], 0
	v_mfma_f32_16x16x32_bf16 v[34:37], v[186:189], v[214:217], 0
	v_mfma_f32_16x16x32_bf16 v[26:29], v[158:161], v[222:225], 0
	v_mfma_f32_16x16x32_bf16 v[18:21], v[186:189], v[222:225], 0
	v_mfma_f32_16x16x32_bf16 v[10:13], v[158:161], v[230:233], 0
	v_mfma_f32_16x16x32_bf16 v[2:5], v[186:189], v[230:233], 0
	v_mfma_f32_16x16x32_bf16 v[62:65], v[146:149], v[210:213], v[62:65]
	v_mfma_f32_16x16x32_bf16 v[54:57], v[154:157], v[210:213], v[54:57]
	v_mfma_f32_16x16x32_bf16 v[46:49], v[146:149], v[218:221], v[46:49]
	v_mfma_f32_16x16x32_bf16 v[38:41], v[154:157], v[218:221], v[38:41]
	v_mfma_f32_16x16x32_bf16 v[30:33], v[146:149], v[226:229], v[30:33]
	v_mfma_f32_16x16x32_bf16 v[22:25], v[154:157], v[226:229], v[22:25]
	v_mfma_f32_16x16x32_bf16 v[14:17], v[146:149], v[234:237], v[14:17]
	v_mfma_f32_16x16x32_bf16 v[6:9], v[154:157], v[234:237], v[6:9]
	v_mfma_f32_16x16x32_bf16 v[58:61], v[178:181], v[210:213], v[58:61]
	v_mfma_f32_16x16x32_bf16 v[50:53], v[202:205], v[210:213], v[50:53]
	v_mfma_f32_16x16x32_bf16 v[42:45], v[178:181], v[218:221], v[42:45]
	v_mfma_f32_16x16x32_bf16 v[34:37], v[202:205], v[218:221], v[34:37]
	v_mfma_f32_16x16x32_bf16 v[26:29], v[178:181], v[226:229], v[26:29]
	v_mfma_f32_16x16x32_bf16 v[18:21], v[202:205], v[226:229], v[18:21]
	v_mfma_f32_16x16x32_bf16 v[10:13], v[178:181], v[234:237], v[10:13]
	v_mfma_f32_16x16x32_bf16 v[2:5], v[202:205], v[234:237], v[2:5]
	s_setprio 0
	s_barrier
	s_add_i32 s22, 0, 0x18000
	s_add_i32 s23, 0, 0x1c000
	v_add_u32_e32 v154, s22, v183
	v_add_u32_e32 v202, s23, v183
	ds_read_b128 v[130:133], v154
	ds_read_b128 v[146:149], v154 offset:1024
	ds_read_b128 v[150:153], v154 offset:2048
	ds_read_b128 v[154:157], v154 offset:3072
	ds_read_b128 v[158:161], v202
	ds_read_b128 v[178:181], v202 offset:1024
	ds_read_b128 v[186:189], v202 offset:2048
	ds_read_b128 v[202:205], v202 offset:3072
	s_add_u32 s14, s14, 0x40000
	s_addc_u32 s15, s15, 0
	s_mov_b32 m0, s30
	v_lshl_add_u64 v[242:243], s[14:15], 0, v[138:139]
	ds_read_b128 v[206:209], v185 offset:32768
	ds_read_b128 v[210:213], v185 offset:33792
	ds_read_b128 v[214:217], v185 offset:34816
	ds_read_b128 v[218:221], v185 offset:35840
	ds_read_b128 v[222:225], v185 offset:36864
	ds_read_b128 v[226:229], v185 offset:37888
	ds_read_b128 v[230:233], v185 offset:38912
	ds_read_b128 v[234:237], v185 offset:39936
	global_load_lds_dwordx4 v[242:243], off
	v_lshl_add_u64 v[242:243], s[14:15], 0, v[136:137]
	s_mov_b32 m0, s31
	s_nop 0
	global_load_lds_dwordx4 v[242:243], off
	s_waitcnt vmcnt(8)
	s_waitcnt lgkmcnt(0)
	s_barrier
	s_setprio 1
	s_waitcnt lgkmcnt(0)
	v_mfma_f32_16x16x32_bf16 v[126:129], v[130:133], v[206:209], v[126:129]
	v_mfma_f32_16x16x32_bf16 v[118:121], v[150:153], v[206:209], v[118:121]
	v_mfma_f32_16x16x32_bf16 v[110:113], v[130:133], v[214:217], v[110:113]
	v_mfma_f32_16x16x32_bf16 v[102:105], v[150:153], v[214:217], v[102:105]
	v_mfma_f32_16x16x32_bf16 v[94:97], v[130:133], v[222:225], v[94:97]
	v_mfma_f32_16x16x32_bf16 v[86:89], v[150:153], v[222:225], v[86:89]
	v_mfma_f32_16x16x32_bf16 v[78:81], v[130:133], v[230:233], v[78:81]
	v_mfma_f32_16x16x32_bf16 v[70:73], v[150:153], v[230:233], v[70:73]
	v_mfma_f32_16x16x32_bf16 v[122:125], v[158:161], v[206:209], v[122:125]
	v_mfma_f32_16x16x32_bf16 v[114:117], v[186:189], v[206:209], v[114:117]
	v_mfma_f32_16x16x32_bf16 v[106:109], v[158:161], v[214:217], v[106:109]
	v_mfma_f32_16x16x32_bf16 v[98:101], v[186:189], v[214:217], v[98:101]
	v_mfma_f32_16x16x32_bf16 v[90:93], v[158:161], v[222:225], v[90:93]
	v_mfma_f32_16x16x32_bf16 v[82:85], v[186:189], v[222:225], v[82:85]
	v_mfma_f32_16x16x32_bf16 v[74:77], v[158:161], v[230:233], v[74:77]
	v_mfma_f32_16x16x32_bf16 v[66:69], v[186:189], v[230:233], v[66:69]
	v_mfma_f32_16x16x32_bf16 v[126:129], v[146:149], v[210:213], v[126:129]
	v_mfma_f32_16x16x32_bf16 v[118:121], v[154:157], v[210:213], v[118:121]
	v_mfma_f32_16x16x32_bf16 v[110:113], v[146:149], v[218:221], v[110:113]
	v_mfma_f32_16x16x32_bf16 v[102:105], v[154:157], v[218:221], v[102:105]
	v_mfma_f32_16x16x32_bf16 v[94:97], v[146:149], v[226:229], v[94:97]
	v_mfma_f32_16x16x32_bf16 v[86:89], v[154:157], v[226:229], v[86:89]
	v_mfma_f32_16x16x32_bf16 v[78:81], v[146:149], v[234:237], v[78:81]
	v_mfma_f32_16x16x32_bf16 v[70:73], v[154:157], v[234:237], v[70:73]
	v_mfma_f32_16x16x32_bf16 v[122:125], v[178:181], v[210:213], v[122:125]
	v_mfma_f32_16x16x32_bf16 v[114:117], v[202:205], v[210:213], v[114:117]
	v_mfma_f32_16x16x32_bf16 v[106:109], v[178:181], v[218:221], v[106:109]
	v_mfma_f32_16x16x32_bf16 v[98:101], v[202:205], v[218:221], v[98:101]
	v_mfma_f32_16x16x32_bf16 v[90:93], v[178:181], v[226:229], v[90:93]
	v_mfma_f32_16x16x32_bf16 v[82:85], v[202:205], v[226:229], v[82:85]
	v_mfma_f32_16x16x32_bf16 v[74:77], v[178:181], v[234:237], v[74:77]
	v_mfma_f32_16x16x32_bf16 v[66:69], v[202:205], v[234:237], v[66:69]
	s_setprio 0
	s_barrier
; #define PG8_STAGE(bufoff, gbase, voff) do { _Pragma("unroll") for (int _i = 0; _i < 2; ++_i) \
;         __builtin_amdgcn_global_load_lds((const unsigned*)((const char*)(gbase) + (voff)[_i]), (PG8_LAS unsigned*)(lds + (bufoff) + ldsw + _i * 8192), 16, 0, 0); } while (0)
; #define PG8_LDA(dst, b, h) do { _Pragma("unroll") for (int m = 0; m < 4; ++m) _Pragma("unroll") for (int k = 0; k < 2; ++k) dst[m][k] = *(const PG8_LAS bf16x8*)(lds + PG8_SA(b, h) + aoff + m * 2048 + k * 1024); } while (0)
; #define PG8_MMA_NP(ai, bj, At, Bt) do { _Pragma("unroll") for (int m = 0; m < 4; ++m) _Pragma("unroll") for (int n = 0; n < 2; ++n) _Pragma("unroll") for (int k = 0; k < 2; ++k) \
;         acc[ai][bj][m][n] = __builtin_amdgcn_mfma_f32_16x16x32_bf16(Bt[n][k], At[m][k], acc[ai][bj][m][n], 0, 0, 0); } while (0)
; #define PG8_WAIT_V(n) asm volatile("s_waitcnt vmcnt(" #n ")" ::: "memory")
; #define PG8_WAIT_L(n) asm volatile("s_waitcnt lgkmcnt(" #n ")" ::: "memory")
; #define PG8_BAR __builtin_amdgcn_s_barrier()
; #define PG8_SCHED __builtin_amdgcn_sched_barrier(0)
; template <class Epi, class Sched, bool ALIGN_EPI = false, bool SP2 = false>
; __device__ __forceinline__ void gemm_phase(PG8_LAS unsigned char* lds, const Gemm g, const Sched& S, const Epi& E) {
;     ...
;             PG8_WAIT_V(8); PG8_WAIT_L(0); PG8_BAR; __builtin_amdgcn_s_setprio(1); PG8_MMA_NP(0, 0, At, B0); PG8_MMA_NP(0, 1, At, B1); __builtin_amdgcn_s_setprio(0); PG8_BAR; PG8_SCHED;
;             PG8_LDA(At, 1, 1); PG8_STAGE(PG8_SB(1, 0), b3, voffB); PG8_STAGE(PG8_SB(1, 1), b3 + hstep, voffB); PG8_STAGE(PG8_SA(1, 0), a3, voffA);
;             PG8_WAIT_V(8); PG8_WAIT_L(0); PG8_BAR; __builtin_amdgcn_s_setprio(1); PG8_MMA_NP(1, 0, At, B0); PG8_MMA_NP(1, 1, At, B1); __builtin_amdgcn_s_setprio(0); PG8_BAR; PG8_SCHED;
	s_add_i32 s14, s22, s8
	v_lshl_add_u64 v[162:163], v[162:163], 0, s[20:21]
	s_mov_b32 m0, s14
	ds_read_b128 v[206:209], v185 offset:49152
	ds_read_b128 v[210:213], v185 offset:50176
	ds_read_b128 v[214:217], v185 offset:51200
	ds_read_b128 v[218:221], v185 offset:52224
	ds_read_b128 v[222:225], v185 offset:53248
	ds_read_b128 v[226:229], v185 offset:54272
	ds_read_b128 v[230:233], v185 offset:55296
	ds_read_b128 v[234:237], v185 offset:56320
	global_load_lds_dwordx4 v[162:163], off
	s_add_i32 m0, s14, 0x2000
	s_add_u32 s12, s12, 0x40080
	v_lshl_add_u64 v[162:163], v[190:191], 0, s[20:21]
	s_addc_u32 s13, s13, 0
	s_add_i32 s14, s23, s8
	global_load_lds_dwordx4 v[162:163], off
	v_lshl_add_u64 v[162:163], s[12:13], 0, v[0:1]
	s_mov_b32 m0, s14
	s_nop 0
	global_load_lds_dwordx4 v[162:163], off
	v_lshl_add_u64 v[162:163], s[12:13], 0, v[134:135]
	s_add_i32 m0, s14, 0x2000
	s_nop 0
	global_load_lds_dwordx4 v[162:163], off
	v_lshl_add_u64 v[162:163], v[238:239], 0, s[20:21]
	s_mov_b32 m0, s54
	s_nop 0
	global_load_lds_dwordx4 v[162:163], off
	v_lshl_add_u64 v[162:163], v[240:241], 0, s[20:21]
	s_mov_b32 m0, s55
	s_nop 0
	global_load_lds_dwordx4 v[162:163], off
	s_waitcnt vmcnt(8)
	s_waitcnt lgkmcnt(0)
	s_barrier
	s_setprio 1
	s_waitcnt lgkmcnt(0)
	v_mfma_f32_16x16x32_bf16 v[62:65], v[130:133], v[206:209], v[62:65]
	v_mfma_f32_16x16x32_bf16 v[54:57], v[150:153], v[206:209], v[54:57]
	v_mfma_f32_16x16x32_bf16 v[46:49], v[130:133], v[214:217], v[46:49]
	v_mfma_f32_16x16x32_bf16 v[38:41], v[150:153], v[214:217], v[38:41]
	v_mfma_f32_16x16x32_bf16 v[30:33], v[130:133], v[222:225], v[30:33]
	v_mfma_f32_16x16x32_bf16 v[22:25], v[150:153], v[222:225], v[22:25]
	v_mfma_f32_16x16x32_bf16 v[14:17], v[130:133], v[230:233], v[14:17]
	v_mfma_f32_16x16x32_bf16 v[6:9], v[150:153], v[230:233], v[6:9]
	v_mfma_f32_16x16x32_bf16 v[58:61], v[158:161], v[206:209], v[58:61]
	v_mfma_f32_16x16x32_bf16 v[50:53], v[186:189], v[206:209], v[50:53]
	v_mfma_f32_16x16x32_bf16 v[42:45], v[158:161], v[214:217], v[42:45]
	v_mfma_f32_16x16x32_bf16 v[34:37], v[186:189], v[214:217], v[34:37]
	v_mfma_f32_16x16x32_bf16 v[26:29], v[158:161], v[222:225], v[26:29]
	v_mfma_f32_16x16x32_bf16 v[18:21], v[186:189], v[222:225], v[18:21]
	v_mfma_f32_16x16x32_bf16 v[10:13], v[158:161], v[230:233], v[10:13]
	v_mfma_f32_16x16x32_bf16 v[2:5], v[186:189], v[230:233], v[2:5]
	v_mfma_f32_16x16x32_bf16 v[62:65], v[146:149], v[210:213], v[62:65]
	v_mfma_f32_16x16x32_bf16 v[54:57], v[154:157], v[210:213], v[54:57]
	v_mfma_f32_16x16x32_bf16 v[46:49], v[146:149], v[218:221], v[46:49]
	v_mfma_f32_16x16x32_bf16 v[38:41], v[154:157], v[218:221], v[38:41]
	v_mfma_f32_16x16x32_bf16 v[30:33], v[146:149], v[226:229], v[30:33]
	v_mfma_f32_16x16x32_bf16 v[22:25], v[154:157], v[226:229], v[22:25]
	v_mfma_f32_16x16x32_bf16 v[14:17], v[146:149], v[234:237], v[14:17]
	v_mfma_f32_16x16x32_bf16 v[6:9], v[154:157], v[234:237], v[6:9]
	v_mfma_f32_16x16x32_bf16 v[58:61], v[178:181], v[210:213], v[58:61]
	v_mfma_f32_16x16x32_bf16 v[50:53], v[202:205], v[210:213], v[50:53]
	v_mfma_f32_16x16x32_bf16 v[42:45], v[178:181], v[218:221], v[42:45]
	v_mfma_f32_16x16x32_bf16 v[34:37], v[202:205], v[218:221], v[34:37]
	v_mfma_f32_16x16x32_bf16 v[26:29], v[178:181], v[226:229], v[26:29]
	v_mfma_f32_16x16x32_bf16 v[18:21], v[202:205], v[226:229], v[18:21]
	v_mfma_f32_16x16x32_bf16 v[10:13], v[178:181], v[234:237], v[10:13]
	v_mfma_f32_16x16x32_bf16 v[2:5], v[202:205], v[234:237], v[2:5]
	s_setprio 0
	s_barrier
	s_add_i32 s63, s63, 2
	s_add_u32 s2, s2, 0x100
	s_addc_u32 s3, s3, 0
	s_add_u32 s61, s61, 0x100
	s_addc_u32 s62, s62, 0
	s_cmp_gt_u32 s63, 13
	s_cbranch_scc0 .LBB0_166
	s_branch .Lkexit_0

; #define PG8_BAR __builtin_amdgcn_s_barrier()
; template <class Epi, class Sched, bool ALIGN_EPI = false, bool SP2 = false>
; __device__ __forceinline__ void gemm_phase(PG8_LAS unsigned char* lds, const Gemm g, const Sched& S, const Epi& E) {
;     ...
;         if constexpr (ALIGN_EPI) { if (wr == 0) PG8_BAR; }
; DI void row_rstd(const float* ssq, int row0, int fq, float (&rs)[2][4]) {
; #pragma unroll
;     for (int ai = 0; ai < 2; ++ai)
; #pragma unroll
;         for (int m = 0; m < 4; ++m) {
;             const f32x4 v = *(const f32x4*)(ssq + (size_t)(row0 + ai * 128 + m * 16) * 16 + 4 * fq);
;             float s = (v[0] + v[1]) + (v[2] + v[3]);
;             s += __shfl_xor(s, 16); s += __shfl_xor(s, 32);
;             rs[ai][m] = rsqrtf(s * (1.0f / DM) + EPS);
;         }
; }
.Lkexit_0:
	v_lshl_add_u32 v234, s58, 8, v182
	v_ashrrev_i32_e32 v235, 31, v234
	v_add_u32_e32 v236, 0x80, v234
	v_ashrrev_i32_e32 v237, 31, v236
	v_lshlrev_b64 v[234:235], 6, v[234:235]
	v_lshlrev_b64 v[236:237], 6, v[236:237]
	v_lshl_add_u64 v[234:235], v[140:141], 0, v[234:235]
	v_lshl_add_u64 v[236:237], v[140:141], 0, v[236:237]
	global_load_dwordx4 v[202:205], v[234:235], off
	global_load_dwordx4 v[206:209], v[234:235], off offset:1024
	global_load_dwordx4 v[210:213], v[234:235], off offset:2048
	global_load_dwordx4 v[214:217], v[234:235], off offset:3072
	global_load_dwordx4 v[218:221], v[236:237], off
	global_load_dwordx4 v[222:225], v[236:237], off offset:1024
	global_load_dwordx4 v[226:229], v[236:237], off offset:2048
	global_load_dwordx4 v[230:233], v[236:237], off offset:3072
	s_and_b64 vcc, exec, s[42:43]
	s_cbranch_vccz .LBB0_169
	s_barrier

; #define PG8_STAGE(bufoff, gbase, voff) do { _Pragma("unroll") for (int _i = 0; _i < 2; ++_i) \
;         __builtin_amdgcn_global_load_lds((const unsigned*)((const char*)(gbase) + (voff)[_i]), (PG8_LAS unsigned*)(lds + (bufoff) + ldsw + _i * 8192), 16, 0, 0); } while (0)
; #define PG8_LDA(dst, b, h) do { _Pragma("unroll") for (int m = 0; m < 4; ++m) _Pragma("unroll") for (int k = 0; k < 2; ++k) dst[m][k] = *(const PG8_LAS bf16x8*)(lds + PG8_SA(b, h) + aoff + m * 2048 + k * 1024); } while (0)
; #define PG8_LDB(dst, b, h) do { _Pragma("unroll") for (int n = 0; n < 2; ++n) _Pragma("unroll") for (int k = 0; k < 2; ++k) dst[n][k] = *(const PG8_LAS bf16x8*)(lds + PG8_SB(b, h) + boff + n * 2048 + k * 1024); } while (0)
; #define PG8_MMA_NP(ai, bj, At, Bt) do { _Pragma("unroll") for (int m = 0; m < 4; ++m) _Pragma("unroll") for (int n = 0; n < 2; ++n) _Pragma("unroll") for (int k = 0; k < 2; ++k) \
;         acc[ai][bj][m][n] = __builtin_amdgcn_mfma_f32_16x16x32_bf16(Bt[n][k], At[m][k], acc[ai][bj][m][n], 0, 0, 0); } while (0)
; #define PG8_WAIT_V(n) asm volatile("s_waitcnt vmcnt(" #n ")" ::: "memory")
; #define PG8_BAR __builtin_amdgcn_s_barrier()
; template <class Epi, class Sched, bool ALIGN_EPI = false, bool SP2 = false>
; __device__ __forceinline__ void gemm_phase(PG8_LAS unsigned char* lds, const Gemm g, const Sched& S, const Epi& E) {
;     ...
;     Unit cur, nxt; int ui = 0;
;     if (!S.next(0, cur)) return;
;     f32x4 acc[2][2][4][2];
; #pragma unroll
;     for (int a = 0; a < 2; ++a)
; #pragma unroll
;         for (int b = 0; b < 2; ++b)
; #pragma unroll
;             for (int m = 0; m < 4; ++m)
; #pragma unroll
;                 for (int n = 0; n < 2; ++n) acc[a][b][m][n] = (f32x4){0.f, 0.f, 0.f, 0.f};
;     ...
;             PG8_LDB(B0, 0, 0); PG8_LDB(B1, 0, 1); PG8_SCHED; PG8_LDA(At, 0, 0); PG8_STAGE(PG8_SA(1, 1), a1 + hstep, voffA);
;             PG8_WAIT_V(8); PG8_WAIT_L(0); PG8_BAR; __builtin_amdgcn_s_setprio(1); PG8_MMA_NP(0, 0, At, B0); PG8_MMA_NP(0, 1, At, B1); __builtin_amdgcn_s_setprio(0); PG8_BAR; PG8_SCHED;
;             PG8_LDA(At, 0, 1); PG8_STAGE(PG8_SB(0, 0), b2, voffB); PG8_STAGE(PG8_SB(0, 1), b2 + hstep, voffB); PG8_STAGE(PG8_SA(0, 0), a2, voffA);
;             PG8_WAIT_V(8); PG8_WAIT_L(0); PG8_BAR; __builtin_amdgcn_s_setprio(1); PG8_MMA_NP(1, 0, At, B0); PG8_MMA_NP(1, 1, At, B1); __builtin_amdgcn_s_setprio(0); PG8_BAR; PG8_SCHED;
.LBB0_369:
	s_ashr_i32 s55, s54, 31
	s_lshl_b64 s[40:41], s[54:55], 19
	s_add_u32 s56, s86, s40
	s_addc_u32 s57, s87, s41
	s_and_b64 s[40:41], s[42:43], exec
	s_cselect_b32 s46, s57, s13
	s_cselect_b32 s47, s56, s12
	s_ashr_i32 s53, s52, 31
	s_lshl_b64 s[40:41], s[52:53], 19
	s_add_u32 s58, s8, s40
	s_addc_u32 s59, s10, s41
	s_and_b64 s[40:41], s[42:43], exec
	s_cselect_b32 s48, s59, s15
	s_cselect_b32 s49, s58, s14
	s_add_u32 s12, s12, 0x40080
	s_addc_u32 s13, s13, 0
	s_add_u32 s53, s14, 0x100
	s_addc_u32 s55, s15, 0
	s_mov_b32 s65, -2
	s_add_u32 s14, s12, 0xfffc0080
	s_addc_u32 s15, s13, -1
	s_add_i32 s22, 0, 0x10000
	s_cmp_eq_u32 s65, 12
	s_cselect_b32 s41, s46, s15
	s_cselect_b32 s40, s47, s14
	s_cselect_b32 s15, s48, s55
	s_cselect_b32 s14, s49, s53
	s_add_i32 s23, 0, 0x14000
	v_add_u32_e32 v154, s22, v191
	v_add_u32_e32 v162, s23, v191
	ds_read_b128 v[130:133], v154
	ds_read_b128 v[146:149], v154 offset:1024
	ds_read_b128 v[150:153], v154 offset:2048
	ds_read_b128 v[154:157], v154 offset:3072
	ds_read_b128 v[158:161], v162
	ds_read_b128 v[178:181], v162 offset:1024
	ds_read_b128 v[182:185], v162 offset:2048
	ds_read_b128 v[186:189], v162 offset:3072
	v_lshl_add_u64 v[162:163], s[12:13], 0, v[142:143]
	s_add_i32 m0, s30, 0xc000
	ds_read_b128 v[204:207], v203
	ds_read_b128 v[208:211], v203 offset:1024
	ds_read_b128 v[212:215], v203 offset:2048
	ds_read_b128 v[216:219], v203 offset:3072
	ds_read_b128 v[220:223], v203 offset:4096
	ds_read_b128 v[224:227], v203 offset:5120
	ds_read_b128 v[228:231], v203 offset:6144
	ds_read_b128 v[232:235], v203 offset:7168
	global_load_lds_dwordx4 v[162:163], off
	v_lshl_add_u64 v[162:163], s[12:13], 0, v[144:145]
	s_add_i32 m0, s30, 0xe000
	s_nop 0
	global_load_lds_dwordx4 v[162:163], off
	s_waitcnt vmcnt(8)
	s_waitcnt lgkmcnt(0)
	s_barrier
	s_setprio 1
	s_waitcnt lgkmcnt(0)
	v_mfma_f32_16x16x32_bf16 v[126:129], v[130:133], v[204:207], 0
	v_mfma_f32_16x16x32_bf16 v[122:125], v[150:153], v[204:207], 0
	v_mfma_f32_16x16x32_bf16 v[110:113], v[130:133], v[212:215], 0
	v_mfma_f32_16x16x32_bf16 v[106:109], v[150:153], v[212:215], 0
	v_mfma_f32_16x16x32_bf16 v[94:97], v[130:133], v[220:223], 0
	v_mfma_f32_16x16x32_bf16 v[90:93], v[150:153], v[220:223], 0
	v_mfma_f32_16x16x32_bf16 v[78:81], v[130:133], v[228:231], 0
	v_mfma_f32_16x16x32_bf16 v[74:77], v[150:153], v[228:231], 0
	v_mfma_f32_16x16x32_bf16 v[118:121], v[158:161], v[204:207], 0
	v_mfma_f32_16x16x32_bf16 v[114:117], v[182:185], v[204:207], 0
	v_mfma_f32_16x16x32_bf16 v[102:105], v[158:161], v[212:215], 0
	v_mfma_f32_16x16x32_bf16 v[98:101], v[182:185], v[212:215], 0
	v_mfma_f32_16x16x32_bf16 v[86:89], v[158:161], v[220:223], 0
	v_mfma_f32_16x16x32_bf16 v[82:85], v[182:185], v[220:223], 0
	v_mfma_f32_16x16x32_bf16 v[70:73], v[158:161], v[228:231], 0
	v_mfma_f32_16x16x32_bf16 v[66:69], v[182:185], v[228:231], 0
	v_mfma_f32_16x16x32_bf16 v[126:129], v[146:149], v[208:211], v[126:129]
	v_mfma_f32_16x16x32_bf16 v[122:125], v[154:157], v[208:211], v[122:125]
	v_mfma_f32_16x16x32_bf16 v[110:113], v[146:149], v[216:219], v[110:113]
	v_mfma_f32_16x16x32_bf16 v[106:109], v[154:157], v[216:219], v[106:109]
	v_mfma_f32_16x16x32_bf16 v[94:97], v[146:149], v[224:227], v[94:97]
	v_mfma_f32_16x16x32_bf16 v[90:93], v[154:157], v[224:227], v[90:93]
	v_mfma_f32_16x16x32_bf16 v[78:81], v[146:149], v[232:235], v[78:81]
	v_mfma_f32_16x16x32_bf16 v[74:77], v[154:157], v[232:235], v[74:77]
	v_mfma_f32_16x16x32_bf16 v[118:121], v[178:181], v[208:211], v[118:121]
	v_mfma_f32_16x16x32_bf16 v[114:117], v[186:189], v[208:211], v[114:117]
	v_mfma_f32_16x16x32_bf16 v[102:105], v[178:181], v[216:219], v[102:105]
	v_mfma_f32_16x16x32_bf16 v[98:101], v[186:189], v[216:219], v[98:101]
	v_mfma_f32_16x16x32_bf16 v[86:89], v[178:181], v[224:227], v[86:89]
	v_mfma_f32_16x16x32_bf16 v[82:85], v[186:189], v[224:227], v[82:85]
	v_mfma_f32_16x16x32_bf16 v[70:73], v[178:181], v[232:235], v[70:73]
	v_mfma_f32_16x16x32_bf16 v[66:69], v[186:189], v[232:235], v[66:69]
	s_setprio 0
	s_barrier
	s_add_i32 s22, s22, s29
	v_lshl_add_u64 v[162:163], s[14:15], 0, v[0:1]
	s_mov_b32 m0, s22
	ds_read_b128 v[204:207], v203 offset:16384
	ds_read_b128 v[208:211], v203 offset:17408
	ds_read_b128 v[212:215], v203 offset:18432
	ds_read_b128 v[216:219], v203 offset:19456
	ds_read_b128 v[220:223], v203 offset:20480
	ds_read_b128 v[224:227], v203 offset:21504
	ds_read_b128 v[228:231], v203 offset:22528
	ds_read_b128 v[232:235], v203 offset:23552
	global_load_lds_dwordx4 v[162:163], off
	s_add_i32 m0, s22, 0x2000
	s_add_u32 s66, s14, 0x40000
	v_lshl_add_u64 v[236:237], s[14:15], 0, v[134:135]
	s_addc_u32 s67, s15, 0
	s_add_i32 s22, s23, s29
	global_load_lds_dwordx4 v[236:237], off
	v_lshl_add_u64 v[238:239], s[66:67], 0, v[0:1]
	s_mov_b32 m0, s22
	v_lshl_add_u64 v[240:241], s[40:41], 0, v[136:137]
	global_load_lds_dwordx4 v[238:239], off
	v_lshl_add_u64 v[238:239], s[66:67], 0, v[134:135]
	s_add_i32 m0, s22, 0x2000
	s_nop 0
	global_load_lds_dwordx4 v[238:239], off
	v_lshl_add_u64 v[238:239], s[40:41], 0, v[138:139]
	s_mov_b32 m0, s30
	s_nop 0
	global_load_lds_dwordx4 v[238:239], off
	s_mov_b32 m0, s31
	s_nop 0
	global_load_lds_dwordx4 v[240:241], off
	s_waitcnt vmcnt(8)
	s_waitcnt lgkmcnt(0)
	s_barrier
; #define PG8_STAGE(bufoff, gbase, voff) do { _Pragma("unroll") for (int _i = 0; _i < 2; ++_i) \
;         __builtin_amdgcn_global_load_lds((const unsigned*)((const char*)(gbase) + (voff)[_i]), (PG8_LAS unsigned*)(lds + (bufoff) + ldsw + _i * 8192), 16, 0, 0); } while (0)
; #define PG8_LDA(dst, b, h) do { _Pragma("unroll") for (int m = 0; m < 4; ++m) _Pragma("unroll") for (int k = 0; k < 2; ++k) dst[m][k] = *(const PG8_LAS bf16x8*)(lds + PG8_SA(b, h) + aoff + m * 2048 + k * 1024); } while (0)
; #define PG8_LDB(dst, b, h) do { _Pragma("unroll") for (int n = 0; n < 2; ++n) _Pragma("unroll") for (int k = 0; k < 2; ++k) dst[n][k] = *(const PG8_LAS bf16x8*)(lds + PG8_SB(b, h) + boff + n * 2048 + k * 1024); } while (0)
; #define PG8_MMA_NP(ai, bj, At, Bt) do { _Pragma("unroll") for (int m = 0; m < 4; ++m) _Pragma("unroll") for (int n = 0; n < 2; ++n) _Pragma("unroll") for (int k = 0; k < 2; ++k) \
;         acc[ai][bj][m][n] = __builtin_amdgcn_mfma_f32_16x16x32_bf16(Bt[n][k], At[m][k], acc[ai][bj][m][n], 0, 0, 0); } while (0)
; #define PG8_WAIT_V(n) asm volatile("s_waitcnt vmcnt(" #n ")" ::: "memory")
; #define PG8_WAIT_L(n) asm volatile("s_waitcnt lgkmcnt(" #n ")" ::: "memory")
; #define PG8_BAR __builtin_amdgcn_s_barrier()
; #define PG8_SCHED __builtin_amdgcn_sched_barrier(0)
; template <class Epi, class Sched, bool ALIGN_EPI = false, bool SP2 = false>
; __device__ __forceinline__ void gemm_phase(PG8_LAS unsigned char* lds, const Gemm g, const Sched& S, const Epi& E) {
;     ...
;             PG8_WAIT_V(8); PG8_WAIT_L(0); PG8_BAR; __builtin_amdgcn_s_setprio(1); PG8_MMA_NP(0, 0, At, B0); PG8_MMA_NP(0, 1, At, B1); __builtin_amdgcn_s_setprio(0); PG8_BAR; PG8_SCHED;
;             PG8_LDA(At, 0, 1); PG8_STAGE(PG8_SB(0, 0), b2, voffB); PG8_STAGE(PG8_SB(0, 1), b2 + hstep, voffB); PG8_STAGE(PG8_SA(0, 0), a2, voffA);
;             PG8_WAIT_V(8); PG8_WAIT_L(0); PG8_BAR; __builtin_amdgcn_s_setprio(1); PG8_MMA_NP(1, 0, At, B0); PG8_MMA_NP(1, 1, At, B1); __builtin_amdgcn_s_setprio(0); PG8_BAR; PG8_SCHED;
;             PG8_LDB(B0, 1, 0); PG8_LDB(B1, 1, 1); PG8_SCHED; PG8_LDA(At, 1, 0); PG8_STAGE(PG8_SA(0, 1), a2 + hstep, voffA);
;             PG8_WAIT_V(8); PG8_WAIT_L(0); PG8_BAR; __builtin_amdgcn_s_setprio(1); PG8_MMA_NP(0, 0, At, B0); PG8_MMA_NP(0, 1, At, B1); __builtin_amdgcn_s_setprio(0); PG8_BAR; PG8_SCHED;
	s_setprio 1
	s_waitcnt lgkmcnt(0)
	v_mfma_f32_16x16x32_bf16 v[62:65], v[130:133], v[204:207], 0
	v_mfma_f32_16x16x32_bf16 v[58:61], v[150:153], v[204:207], 0
	v_mfma_f32_16x16x32_bf16 v[46:49], v[130:133], v[212:215], 0
	v_mfma_f32_16x16x32_bf16 v[42:45], v[150:153], v[212:215], 0
	v_mfma_f32_16x16x32_bf16 v[30:33], v[130:133], v[220:223], 0
	v_mfma_f32_16x16x32_bf16 v[26:29], v[150:153], v[220:223], 0
	v_mfma_f32_16x16x32_bf16 v[14:17], v[130:133], v[228:231], 0
	v_mfma_f32_16x16x32_bf16 v[10:13], v[150:153], v[228:231], 0
	v_mfma_f32_16x16x32_bf16 v[54:57], v[158:161], v[204:207], 0
	v_mfma_f32_16x16x32_bf16 v[50:53], v[182:185], v[204:207], 0
	v_mfma_f32_16x16x32_bf16 v[38:41], v[158:161], v[212:215], 0
	v_mfma_f32_16x16x32_bf16 v[34:37], v[182:185], v[212:215], 0
	v_mfma_f32_16x16x32_bf16 v[22:25], v[158:161], v[220:223], 0
	v_mfma_f32_16x16x32_bf16 v[18:21], v[182:185], v[220:223], 0
	v_mfma_f32_16x16x32_bf16 v[6:9], v[158:161], v[228:231], 0
	v_mfma_f32_16x16x32_bf16 v[2:5], v[182:185], v[228:231], 0
	v_mfma_f32_16x16x32_bf16 v[62:65], v[146:149], v[208:211], v[62:65]
	v_mfma_f32_16x16x32_bf16 v[58:61], v[154:157], v[208:211], v[58:61]
	v_mfma_f32_16x16x32_bf16 v[46:49], v[146:149], v[216:219], v[46:49]
	v_mfma_f32_16x16x32_bf16 v[42:45], v[154:157], v[216:219], v[42:45]
	v_mfma_f32_16x16x32_bf16 v[30:33], v[146:149], v[224:227], v[30:33]
	v_mfma_f32_16x16x32_bf16 v[26:29], v[154:157], v[224:227], v[26:29]
	v_mfma_f32_16x16x32_bf16 v[14:17], v[146:149], v[232:235], v[14:17]
	v_mfma_f32_16x16x32_bf16 v[10:13], v[154:157], v[232:235], v[10:13]
	v_mfma_f32_16x16x32_bf16 v[54:57], v[178:181], v[208:211], v[54:57]
	v_mfma_f32_16x16x32_bf16 v[50:53], v[186:189], v[208:211], v[50:53]
	v_mfma_f32_16x16x32_bf16 v[38:41], v[178:181], v[216:219], v[38:41]
	v_mfma_f32_16x16x32_bf16 v[34:37], v[186:189], v[216:219], v[34:37]
	v_mfma_f32_16x16x32_bf16 v[22:25], v[178:181], v[224:227], v[22:25]
	v_mfma_f32_16x16x32_bf16 v[18:21], v[186:189], v[224:227], v[18:21]
	v_mfma_f32_16x16x32_bf16 v[6:9], v[178:181], v[232:235], v[6:9]
	v_mfma_f32_16x16x32_bf16 v[2:5], v[186:189], v[232:235], v[2:5]
	s_setprio 0
	s_barrier
	s_add_i32 s22, 0, 0x18000
	s_add_i32 s23, 0, 0x1c000
	v_add_u32_e32 v154, s22, v191
	v_add_u32_e32 v186, s23, v191
	ds_read_b128 v[130:133], v154
	ds_read_b128 v[146:149], v154 offset:1024
	ds_read_b128 v[150:153], v154 offset:2048
	ds_read_b128 v[154:157], v154 offset:3072
	ds_read_b128 v[158:161], v186
	ds_read_b128 v[178:181], v186 offset:1024
	ds_read_b128 v[182:185], v186 offset:2048
	ds_read_b128 v[186:189], v186 offset:3072
	s_add_u32 s40, s40, 0x40000
	s_addc_u32 s41, s41, 0
	s_mov_b32 m0, s60
	v_lshl_add_u64 v[242:243], s[40:41], 0, v[138:139]
	ds_read_b128 v[204:207], v203 offset:32768
	ds_read_b128 v[208:211], v203 offset:33792
	ds_read_b128 v[212:215], v203 offset:34816
	ds_read_b128 v[216:219], v203 offset:35840
	ds_read_b128 v[220:223], v203 offset:36864
	ds_read_b128 v[224:227], v203 offset:37888
	ds_read_b128 v[228:231], v203 offset:38912
	ds_read_b128 v[232:235], v203 offset:39936
	global_load_lds_dwordx4 v[242:243], off
	v_lshl_add_u64 v[242:243], s[40:41], 0, v[136:137]
	s_mov_b32 m0, s61
	s_nop 0
	global_load_lds_dwordx4 v[242:243], off
	s_waitcnt vmcnt(8)
	s_waitcnt lgkmcnt(0)
	s_barrier
	s_setprio 1
	s_waitcnt lgkmcnt(0)
	v_mfma_f32_16x16x32_bf16 v[126:129], v[130:133], v[204:207], v[126:129]
	v_mfma_f32_16x16x32_bf16 v[122:125], v[150:153], v[204:207], v[122:125]
	v_mfma_f32_16x16x32_bf16 v[110:113], v[130:133], v[212:215], v[110:113]
	v_mfma_f32_16x16x32_bf16 v[106:109], v[150:153], v[212:215], v[106:109]
	v_mfma_f32_16x16x32_bf16 v[94:97], v[130:133], v[220:223], v[94:97]
	v_mfma_f32_16x16x32_bf16 v[90:93], v[150:153], v[220:223], v[90:93]
	v_mfma_f32_16x16x32_bf16 v[78:81], v[130:133], v[228:231], v[78:81]
	v_mfma_f32_16x16x32_bf16 v[74:77], v[150:153], v[228:231], v[74:77]
	v_mfma_f32_16x16x32_bf16 v[118:121], v[158:161], v[204:207], v[118:121]
	v_mfma_f32_16x16x32_bf16 v[114:117], v[182:185], v[204:207], v[114:117]
	v_mfma_f32_16x16x32_bf16 v[102:105], v[158:161], v[212:215], v[102:105]
	v_mfma_f32_16x16x32_bf16 v[98:101], v[182:185], v[212:215], v[98:101]
	v_mfma_f32_16x16x32_bf16 v[86:89], v[158:161], v[220:223], v[86:89]
	v_mfma_f32_16x16x32_bf16 v[82:85], v[182:185], v[220:223], v[82:85]
	v_mfma_f32_16x16x32_bf16 v[70:73], v[158:161], v[228:231], v[70:73]
	v_mfma_f32_16x16x32_bf16 v[66:69], v[182:185], v[228:231], v[66:69]
	v_mfma_f32_16x16x32_bf16 v[126:129], v[146:149], v[208:211], v[126:129]
	v_mfma_f32_16x16x32_bf16 v[122:125], v[154:157], v[208:211], v[122:125]
	v_mfma_f32_16x16x32_bf16 v[110:113], v[146:149], v[216:219], v[110:113]
	v_mfma_f32_16x16x32_bf16 v[106:109], v[154:157], v[216:219], v[106:109]
	v_mfma_f32_16x16x32_bf16 v[94:97], v[146:149], v[224:227], v[94:97]
	v_mfma_f32_16x16x32_bf16 v[90:93], v[154:157], v[224:227], v[90:93]
	v_mfma_f32_16x16x32_bf16 v[78:81], v[146:149], v[232:235], v[78:81]
	v_mfma_f32_16x16x32_bf16 v[74:77], v[154:157], v[232:235], v[74:77]
	v_mfma_f32_16x16x32_bf16 v[118:121], v[178:181], v[208:211], v[118:121]
	v_mfma_f32_16x16x32_bf16 v[114:117], v[186:189], v[208:211], v[114:117]
	v_mfma_f32_16x16x32_bf16 v[102:105], v[178:181], v[216:219], v[102:105]
	v_mfma_f32_16x16x32_bf16 v[98:101], v[186:189], v[216:219], v[98:101]
	v_mfma_f32_16x16x32_bf16 v[86:89], v[178:181], v[224:227], v[86:89]
	v_mfma_f32_16x16x32_bf16 v[82:85], v[186:189], v[224:227], v[82:85]
	v_mfma_f32_16x16x32_bf16 v[70:73], v[178:181], v[232:235], v[70:73]
	v_mfma_f32_16x16x32_bf16 v[66:69], v[186:189], v[232:235], v[66:69]
	s_setprio 0
	s_barrier
; #define PG8_STAGE(bufoff, gbase, voff) do { _Pragma("unroll") for (int _i = 0; _i < 2; ++_i) \
;         __builtin_amdgcn_global_load_lds((const unsigned*)((const char*)(gbase) + (voff)[_i]), (PG8_LAS unsigned*)(lds + (bufoff) + ldsw + _i * 8192), 16, 0, 0); } while (0)
; #define PG8_LDA(dst, b, h) do { _Pragma("unroll") for (int m = 0; m < 4; ++m) _Pragma("unroll") for (int k = 0; k < 2; ++k) dst[m][k] = *(const PG8_LAS bf16x8*)(lds + PG8_SA(b, h) + aoff + m * 2048 + k * 1024); } while (0)
; #define PG8_MMA_NP(ai, bj, At, Bt) do { _Pragma("unroll") for (int m = 0; m < 4; ++m) _Pragma("unroll") for (int n = 0; n < 2; ++n) _Pragma("unroll") for (int k = 0; k < 2; ++k) \
;         acc[ai][bj][m][n] = __builtin_amdgcn_mfma_f32_16x16x32_bf16(Bt[n][k], At[m][k], acc[ai][bj][m][n], 0, 0, 0); } while (0)
; #define PG8_WAIT_V(n) asm volatile("s_waitcnt vmcnt(" #n ")" ::: "memory")
; #define PG8_WAIT_L(n) asm volatile("s_waitcnt lgkmcnt(" #n ")" ::: "memory")
; #define PG8_BAR __builtin_amdgcn_s_barrier()
; #define PG8_SCHED __builtin_amdgcn_sched_barrier(0)
; template <class Epi, class Sched, bool ALIGN_EPI = false, bool SP2 = false>
; __device__ __forceinline__ void gemm_phase(PG8_LAS unsigned char* lds, const Gemm g, const Sched& S, const Epi& E) {
;     ...
;             PG8_WAIT_V(8); PG8_WAIT_L(0); PG8_BAR; __builtin_amdgcn_s_setprio(1); PG8_MMA_NP(0, 0, At, B0); PG8_MMA_NP(0, 1, At, B1); __builtin_amdgcn_s_setprio(0); PG8_BAR; PG8_SCHED;
;             PG8_LDA(At, 1, 1); PG8_STAGE(PG8_SB(1, 0), b3, voffB); PG8_STAGE(PG8_SB(1, 1), b3 + hstep, voffB); PG8_STAGE(PG8_SA(1, 0), a3, voffA);
;             PG8_WAIT_V(8); PG8_WAIT_L(0); PG8_BAR; __builtin_amdgcn_s_setprio(1); PG8_MMA_NP(1, 0, At, B0); PG8_MMA_NP(1, 1, At, B1); __builtin_amdgcn_s_setprio(0); PG8_BAR; PG8_SCHED;
	s_add_i32 s22, s22, s29
	v_lshl_add_u64 v[162:163], v[162:163], 0, s[20:21]
	s_mov_b32 m0, s22
	ds_read_b128 v[204:207], v203 offset:49152
	ds_read_b128 v[208:211], v203 offset:50176
	ds_read_b128 v[212:215], v203 offset:51200
	ds_read_b128 v[216:219], v203 offset:52224
	ds_read_b128 v[220:223], v203 offset:53248
	ds_read_b128 v[224:227], v203 offset:54272
	ds_read_b128 v[228:231], v203 offset:55296
	ds_read_b128 v[232:235], v203 offset:56320
	global_load_lds_dwordx4 v[162:163], off
	s_add_i32 m0, s22, 0x2000
	s_add_u32 s14, s14, 0x40080
	v_lshl_add_u64 v[162:163], v[236:237], 0, s[20:21]
	s_addc_u32 s15, s15, 0
	s_add_i32 s22, s23, s29
	global_load_lds_dwordx4 v[162:163], off
	v_lshl_add_u64 v[162:163], s[14:15], 0, v[0:1]
	s_mov_b32 m0, s22
	s_nop 0
	global_load_lds_dwordx4 v[162:163], off
	v_lshl_add_u64 v[162:163], s[14:15], 0, v[134:135]
	s_add_i32 m0, s22, 0x2000
	s_nop 0
	global_load_lds_dwordx4 v[162:163], off
	v_lshl_add_u64 v[162:163], v[238:239], 0, s[20:21]
	s_mov_b32 m0, s62
	s_nop 0
	global_load_lds_dwordx4 v[162:163], off
	v_lshl_add_u64 v[162:163], v[240:241], 0, s[20:21]
	s_mov_b32 m0, s63
	s_nop 0
	global_load_lds_dwordx4 v[162:163], off
	s_waitcnt vmcnt(8)
	s_waitcnt lgkmcnt(0)
	s_barrier
	s_setprio 1
	s_waitcnt lgkmcnt(0)
	v_mfma_f32_16x16x32_bf16 v[62:65], v[130:133], v[204:207], v[62:65]
	v_mfma_f32_16x16x32_bf16 v[58:61], v[150:153], v[204:207], v[58:61]
	v_mfma_f32_16x16x32_bf16 v[46:49], v[130:133], v[212:215], v[46:49]
	v_mfma_f32_16x16x32_bf16 v[42:45], v[150:153], v[212:215], v[42:45]
	v_mfma_f32_16x16x32_bf16 v[30:33], v[130:133], v[220:223], v[30:33]
	v_mfma_f32_16x16x32_bf16 v[26:29], v[150:153], v[220:223], v[26:29]
	v_mfma_f32_16x16x32_bf16 v[14:17], v[130:133], v[228:231], v[14:17]
	v_mfma_f32_16x16x32_bf16 v[10:13], v[150:153], v[228:231], v[10:13]
	v_mfma_f32_16x16x32_bf16 v[54:57], v[158:161], v[204:207], v[54:57]
	v_mfma_f32_16x16x32_bf16 v[50:53], v[182:185], v[204:207], v[50:53]
	v_mfma_f32_16x16x32_bf16 v[38:41], v[158:161], v[212:215], v[38:41]
	v_mfma_f32_16x16x32_bf16 v[34:37], v[182:185], v[212:215], v[34:37]
	v_mfma_f32_16x16x32_bf16 v[22:25], v[158:161], v[220:223], v[22:25]
	v_mfma_f32_16x16x32_bf16 v[18:21], v[182:185], v[220:223], v[18:21]
	v_mfma_f32_16x16x32_bf16 v[6:9], v[158:161], v[228:231], v[6:9]
	v_mfma_f32_16x16x32_bf16 v[2:5], v[182:185], v[228:231], v[2:5]
	v_mfma_f32_16x16x32_bf16 v[62:65], v[146:149], v[208:211], v[62:65]
	v_mfma_f32_16x16x32_bf16 v[58:61], v[154:157], v[208:211], v[58:61]
	v_mfma_f32_16x16x32_bf16 v[46:49], v[146:149], v[216:219], v[46:49]
	v_mfma_f32_16x16x32_bf16 v[42:45], v[154:157], v[216:219], v[42:45]
	v_mfma_f32_16x16x32_bf16 v[30:33], v[146:149], v[224:227], v[30:33]
	v_mfma_f32_16x16x32_bf16 v[26:29], v[154:157], v[224:227], v[26:29]
	v_mfma_f32_16x16x32_bf16 v[14:17], v[146:149], v[232:235], v[14:17]
	v_mfma_f32_16x16x32_bf16 v[10:13], v[154:157], v[232:235], v[10:13]
	v_mfma_f32_16x16x32_bf16 v[54:57], v[178:181], v[208:211], v[54:57]
	v_mfma_f32_16x16x32_bf16 v[50:53], v[186:189], v[208:211], v[50:53]
	v_mfma_f32_16x16x32_bf16 v[38:41], v[178:181], v[216:219], v[38:41]
	v_mfma_f32_16x16x32_bf16 v[34:37], v[186:189], v[216:219], v[34:37]
	v_mfma_f32_16x16x32_bf16 v[22:25], v[178:181], v[224:227], v[22:25]
	v_mfma_f32_16x16x32_bf16 v[18:21], v[186:189], v[224:227], v[18:21]
	v_mfma_f32_16x16x32_bf16 v[6:9], v[178:181], v[232:235], v[6:9]
	v_mfma_f32_16x16x32_bf16 v[2:5], v[186:189], v[232:235], v[2:5]
	s_setprio 0
	s_barrier
	s_add_i32 s65, s65, 2
	s_add_u32 s12, s12, 0x100
	s_addc_u32 s13, s13, 0
	s_add_u32 s53, s53, 0x100
	s_addc_u32 s55, s55, 0
	s_cmp_gt_u32 s65, 13
	s_cbranch_scc0 .LBB0_370
	s_branch .Lkexit_2

; #define PG8_BAR __builtin_amdgcn_s_barrier()
; template <class Epi, class Sched, bool ALIGN_EPI = false, bool SP2 = false>
; __device__ __forceinline__ void gemm_phase(PG8_LAS unsigned char* lds, const Gemm g, const Sched& S, const Epi& E) {
;     ...
;         if constexpr (ALIGN_EPI) { if (wr == 0) PG8_BAR; }
; DI void row_rstd(const float* ssq, int row0, int fq, float (&rs)[2][4]) {
; #pragma unroll
;     for (int ai = 0; ai < 2; ++ai)
; #pragma unroll
;         for (int m = 0; m < 4; ++m) {
;             const f32x4 v = *(const f32x4*)(ssq + (size_t)(row0 + ai * 128 + m * 16) * 16 + 4 * fq);
;             float s = (v[0] + v[1]) + (v[2] + v[3]);
;             s += __shfl_xor(s, 16); s += __shfl_xor(s, 32);
;             rs[ai][m] = rsqrtf(s * (1.0f / DM) + EPS);
;         }
; }
.Lkexit_2:
	v_lshl_add_u32 v240, s45, 8, v190
	v_ashrrev_i32_e32 v241, 31, v240
	v_add_u32_e32 v242, 0x80, v240
	v_ashrrev_i32_e32 v243, 31, v242
	v_lshlrev_b64 v[240:241], 6, v[240:241]
	v_lshlrev_b64 v[242:243], 6, v[242:243]
	v_lshl_add_u64 v[240:241], v[140:141], 0, v[240:241]
	v_lshl_add_u64 v[242:243], v[140:141], 0, v[242:243]
	global_load_dwordx4 v[208:211], v[240:241], off
	global_load_dwordx4 v[212:215], v[240:241], off offset:1024
	global_load_dwordx4 v[216:219], v[240:241], off offset:2048
	global_load_dwordx4 v[220:223], v[240:241], off offset:3072
	global_load_dwordx4 v[224:227], v[242:243], off
	global_load_dwordx4 v[228:231], v[242:243], off offset:1024
	global_load_dwordx4 v[232:235], v[242:243], off offset:2048
	global_load_dwordx4 v[236:239], v[242:243], off offset:3072
	s_and_b64 vcc, exec, s[38:39]
	s_cbranch_vccz .LBB0_373
	s_barrier

; #define PG8_STAGE(bufoff, gbase, voff) do { _Pragma("unroll") for (int _i = 0; _i < 2; ++_i) \
;         __builtin_amdgcn_global_load_lds((const unsigned*)((const char*)(gbase) + (voff)[_i]), (PG8_LAS unsigned*)(lds + (bufoff) + ldsw + _i * 8192), 16, 0, 0); } while (0)
; #define PG8_LDA(dst, b, h) do { _Pragma("unroll") for (int m = 0; m < 4; ++m) _Pragma("unroll") for (int k = 0; k < 2; ++k) dst[m][k] = *(const PG8_LAS bf16x8*)(lds + PG8_SA(b, h) + aoff + m * 2048 + k * 1024); } while (0)
; #define PG8_LDB(dst, b, h) do { _Pragma("unroll") for (int n = 0; n < 2; ++n) _Pragma("unroll") for (int k = 0; k < 2; ++k) dst[n][k] = *(const PG8_LAS bf16x8*)(lds + PG8_SB(b, h) + boff + n * 2048 + k * 1024); } while (0)
; #define PG8_MMA_NP(ai, bj, At, Bt) do { _Pragma("unroll") for (int m = 0; m < 4; ++m) _Pragma("unroll") for (int n = 0; n < 2; ++n) _Pragma("unroll") for (int k = 0; k < 2; ++k) \
;         acc[ai][bj][m][n] = __builtin_amdgcn_mfma_f32_16x16x32_bf16(Bt[n][k], At[m][k], acc[ai][bj][m][n], 0, 0, 0); } while (0)
; #define PG8_WAIT_V(n) asm volatile("s_waitcnt vmcnt(" #n ")" ::: "memory")
; #define PG8_BAR __builtin_amdgcn_s_barrier()
; template <class Epi, class Sched, bool ALIGN_EPI = false, bool SP2 = false>
; __device__ __forceinline__ void gemm_phase(PG8_LAS unsigned char* lds, const Gemm g, const Sched& S, const Epi& E) {
;     ...
;     Unit cur, nxt; int ui = 0;
;     if (!S.next(0, cur)) return;
;     f32x4 acc[2][2][4][2];
; #pragma unroll
;     for (int a = 0; a < 2; ++a)
; #pragma unroll
;         for (int b = 0; b < 2; ++b)
; #pragma unroll
;             for (int m = 0; m < 4; ++m)
; #pragma unroll
;                 for (int n = 0; n < 2; ++n) acc[a][b][m][n] = (f32x4){0.f, 0.f, 0.f, 0.f};
;     ...
;             PG8_LDB(B0, 0, 0); PG8_LDB(B1, 0, 1); PG8_SCHED; PG8_LDA(At, 0, 0); PG8_STAGE(PG8_SA(1, 1), a1 + hstep, voffA);
;             PG8_WAIT_V(8); PG8_WAIT_L(0); PG8_BAR; __builtin_amdgcn_s_setprio(1); PG8_MMA_NP(0, 0, At, B0); PG8_MMA_NP(0, 1, At, B1); __builtin_amdgcn_s_setprio(0); PG8_BAR; PG8_SCHED;
;             PG8_LDA(At, 0, 1); PG8_STAGE(PG8_SB(0, 0), b2, voffB); PG8_STAGE(PG8_SB(0, 1), b2 + hstep, voffB); PG8_STAGE(PG8_SA(0, 0), a2, voffA);
;             PG8_WAIT_V(8); PG8_WAIT_L(0); PG8_BAR; __builtin_amdgcn_s_setprio(1); PG8_MMA_NP(1, 0, At, B0); PG8_MMA_NP(1, 1, At, B1); __builtin_amdgcn_s_setprio(0); PG8_BAR; PG8_SCHED;
.LBB0_431:
	s_ashr_i32 s49, s48, 31
	s_lshl_b64 s[14:15], s[48:49], 19
	s_add_u32 s50, s10, s14
	s_addc_u32 s51, s29, s15
	s_and_b64 s[14:15], s[42:43], exec
	s_cselect_b32 s49, s51, s3
	s_cselect_b32 s59, s50, s2
	s_ashr_i32 s47, s46, 31
	s_lshl_b64 s[14:15], s[46:47], 19
	s_add_u32 s52, s86, s14
	s_addc_u32 s53, s87, s15
	s_and_b64 s[14:15], s[42:43], exec
	s_cselect_b32 s47, s53, s13
	s_cselect_b32 s60, s52, s12
	s_add_u32 s2, s2, 0x40080
	s_addc_u32 s3, s3, 0
	s_add_u32 s61, s12, 0x100
	s_addc_u32 s62, s13, 0
	s_mov_b32 s63, -2
	s_add_u32 s12, s2, 0xfffc0080
	s_addc_u32 s13, s3, -1
	s_add_i32 s22, 0, 0x10000
	s_cmp_eq_u32 s63, 12
	s_cselect_b32 s15, s49, s13
	s_cselect_b32 s14, s59, s12
	s_cselect_b32 s13, s47, s62
	s_cselect_b32 s12, s60, s61
	s_add_i32 s23, 0, 0x14000
	v_add_u32_e32 v154, s22, v159
	v_add_u32_e32 v162, s23, v159
	ds_read_b128 v[142:145], v154
	ds_read_b128 v[146:149], v154 offset:1024
	ds_read_b128 v[150:153], v154 offset:2048
	ds_read_b128 v[154:157], v154 offset:3072
	ds_read_b128 v[178:181], v162
	ds_read_b128 v[182:185], v162 offset:1024
	ds_read_b128 v[186:189], v162 offset:2048
	ds_read_b128 v[202:205], v162 offset:3072
	v_lshl_add_u64 v[162:163], s[2:3], 0, v[138:139]
	s_add_i32 m0, s30, 0xc000
	ds_read_b128 v[206:209], v161
	ds_read_b128 v[210:213], v161 offset:1024
	ds_read_b128 v[214:217], v161 offset:2048
	ds_read_b128 v[218:221], v161 offset:3072
	ds_read_b128 v[222:225], v161 offset:4096
	ds_read_b128 v[226:229], v161 offset:5120
	ds_read_b128 v[230:233], v161 offset:6144
	ds_read_b128 v[234:237], v161 offset:7168
	global_load_lds_dwordx4 v[162:163], off
	v_lshl_add_u64 v[162:163], s[2:3], 0, v[140:141]
	s_add_i32 m0, s30, 0xe000
	s_nop 0
	global_load_lds_dwordx4 v[162:163], off
	s_waitcnt vmcnt(8)
	s_waitcnt lgkmcnt(0)
	s_barrier
	s_setprio 1
	s_waitcnt lgkmcnt(0)
	v_mfma_f32_16x16x32_bf16 v[126:129], v[142:145], v[206:209], 0
	v_mfma_f32_16x16x32_bf16 v[122:125], v[150:153], v[206:209], 0
	v_mfma_f32_16x16x32_bf16 v[118:121], v[142:145], v[214:217], 0
	v_mfma_f32_16x16x32_bf16 v[114:117], v[150:153], v[214:217], 0
	v_mfma_f32_16x16x32_bf16 v[110:113], v[142:145], v[222:225], 0
	v_mfma_f32_16x16x32_bf16 v[106:109], v[150:153], v[222:225], 0
	v_mfma_f32_16x16x32_bf16 v[102:105], v[142:145], v[230:233], 0
	v_mfma_f32_16x16x32_bf16 v[98:101], v[150:153], v[230:233], 0
	v_mfma_f32_16x16x32_bf16 v[62:65], v[178:181], v[206:209], 0
	v_mfma_f32_16x16x32_bf16 v[58:61], v[186:189], v[206:209], 0
	v_mfma_f32_16x16x32_bf16 v[54:57], v[178:181], v[214:217], 0
	v_mfma_f32_16x16x32_bf16 v[50:53], v[186:189], v[214:217], 0
	v_mfma_f32_16x16x32_bf16 v[46:49], v[178:181], v[222:225], 0
	v_mfma_f32_16x16x32_bf16 v[42:45], v[186:189], v[222:225], 0
	v_mfma_f32_16x16x32_bf16 v[38:41], v[178:181], v[230:233], 0
	v_mfma_f32_16x16x32_bf16 v[34:37], v[186:189], v[230:233], 0
	v_mfma_f32_16x16x32_bf16 v[126:129], v[146:149], v[210:213], v[126:129]
	v_mfma_f32_16x16x32_bf16 v[122:125], v[154:157], v[210:213], v[122:125]
	v_mfma_f32_16x16x32_bf16 v[118:121], v[146:149], v[218:221], v[118:121]
	v_mfma_f32_16x16x32_bf16 v[114:117], v[154:157], v[218:221], v[114:117]
	v_mfma_f32_16x16x32_bf16 v[110:113], v[146:149], v[226:229], v[110:113]
	v_mfma_f32_16x16x32_bf16 v[106:109], v[154:157], v[226:229], v[106:109]
	v_mfma_f32_16x16x32_bf16 v[102:105], v[146:149], v[234:237], v[102:105]
	v_mfma_f32_16x16x32_bf16 v[98:101], v[154:157], v[234:237], v[98:101]
	v_mfma_f32_16x16x32_bf16 v[62:65], v[182:185], v[210:213], v[62:65]
	v_mfma_f32_16x16x32_bf16 v[58:61], v[202:205], v[210:213], v[58:61]
	v_mfma_f32_16x16x32_bf16 v[54:57], v[182:185], v[218:221], v[54:57]
	v_mfma_f32_16x16x32_bf16 v[50:53], v[202:205], v[218:221], v[50:53]
	v_mfma_f32_16x16x32_bf16 v[46:49], v[182:185], v[226:229], v[46:49]
	v_mfma_f32_16x16x32_bf16 v[42:45], v[202:205], v[226:229], v[42:45]
	v_mfma_f32_16x16x32_bf16 v[38:41], v[182:185], v[234:237], v[38:41]
	v_mfma_f32_16x16x32_bf16 v[34:37], v[202:205], v[234:237], v[34:37]
	s_setprio 0
	s_barrier
	s_add_i32 s22, s22, s8
	v_lshl_add_u64 v[162:163], s[12:13], 0, v[0:1]
	s_mov_b32 m0, s22
	ds_read_b128 v[206:209], v161 offset:16384
	ds_read_b128 v[210:213], v161 offset:17408
	ds_read_b128 v[214:217], v161 offset:18432
	ds_read_b128 v[218:221], v161 offset:19456
	ds_read_b128 v[222:225], v161 offset:20480
	ds_read_b128 v[226:229], v161 offset:21504
	ds_read_b128 v[230:233], v161 offset:22528
	ds_read_b128 v[234:237], v161 offset:23552
	global_load_lds_dwordx4 v[162:163], off
	s_add_i32 m0, s22, 0x2000
	s_add_u32 s64, s12, 0x40000
	v_lshl_add_u64 v[190:191], s[12:13], 0, v[130:131]
	s_addc_u32 s65, s13, 0
	s_add_i32 s22, s23, s8
	global_load_lds_dwordx4 v[190:191], off
	v_lshl_add_u64 v[238:239], s[64:65], 0, v[0:1]
	s_mov_b32 m0, s22
	v_lshl_add_u64 v[240:241], s[14:15], 0, v[132:133]
	global_load_lds_dwordx4 v[238:239], off
	v_lshl_add_u64 v[238:239], s[64:65], 0, v[130:131]
	s_add_i32 m0, s22, 0x2000
	s_nop 0
	global_load_lds_dwordx4 v[238:239], off
	v_lshl_add_u64 v[238:239], s[14:15], 0, v[134:135]
	s_mov_b32 m0, s30
	s_nop 0
	global_load_lds_dwordx4 v[238:239], off
	s_mov_b32 m0, s31
	s_nop 0
	global_load_lds_dwordx4 v[240:241], off
	s_waitcnt vmcnt(8)
	s_waitcnt lgkmcnt(0)
	s_barrier
; #define PG8_STAGE(bufoff, gbase, voff) do { _Pragma("unroll") for (int _i = 0; _i < 2; ++_i) \
;         __builtin_amdgcn_global_load_lds((const unsigned*)((const char*)(gbase) + (voff)[_i]), (PG8_LAS unsigned*)(lds + (bufoff) + ldsw + _i * 8192), 16, 0, 0); } while (0)
; #define PG8_LDA(dst, b, h) do { _Pragma("unroll") for (int m = 0; m < 4; ++m) _Pragma("unroll") for (int k = 0; k < 2; ++k) dst[m][k] = *(const PG8_LAS bf16x8*)(lds + PG8_SA(b, h) + aoff + m * 2048 + k * 1024); } while (0)
; #define PG8_LDB(dst, b, h) do { _Pragma("unroll") for (int n = 0; n < 2; ++n) _Pragma("unroll") for (int k = 0; k < 2; ++k) dst[n][k] = *(const PG8_LAS bf16x8*)(lds + PG8_SB(b, h) + boff + n * 2048 + k * 1024); } while (0)
; #define PG8_MMA_NP(ai, bj, At, Bt) do { _Pragma("unroll") for (int m = 0; m < 4; ++m) _Pragma("unroll") for (int n = 0; n < 2; ++n) _Pragma("unroll") for (int k = 0; k < 2; ++k) \
;         acc[ai][bj][m][n] = __builtin_amdgcn_mfma_f32_16x16x32_bf16(Bt[n][k], At[m][k], acc[ai][bj][m][n], 0, 0, 0); } while (0)
; #define PG8_WAIT_V(n) asm volatile("s_waitcnt vmcnt(" #n ")" ::: "memory")
; #define PG8_WAIT_L(n) asm volatile("s_waitcnt lgkmcnt(" #n ")" ::: "memory")
; #define PG8_BAR __builtin_amdgcn_s_barrier()
; #define PG8_SCHED __builtin_amdgcn_sched_barrier(0)
; template <class Epi, class Sched, bool ALIGN_EPI = false, bool SP2 = false>
; __device__ __forceinline__ void gemm_phase(PG8_LAS unsigned char* lds, const Gemm g, const Sched& S, const Epi& E) {
;     ...
;             PG8_WAIT_V(8); PG8_WAIT_L(0); PG8_BAR; __builtin_amdgcn_s_setprio(1); PG8_MMA_NP(0, 0, At, B0); PG8_MMA_NP(0, 1, At, B1); __builtin_amdgcn_s_setprio(0); PG8_BAR; PG8_SCHED;
;             PG8_LDA(At, 0, 1); PG8_STAGE(PG8_SB(0, 0), b2, voffB); PG8_STAGE(PG8_SB(0, 1), b2 + hstep, voffB); PG8_STAGE(PG8_SA(0, 0), a2, voffA);
;             PG8_WAIT_V(8); PG8_WAIT_L(0); PG8_BAR; __builtin_amdgcn_s_setprio(1); PG8_MMA_NP(1, 0, At, B0); PG8_MMA_NP(1, 1, At, B1); __builtin_amdgcn_s_setprio(0); PG8_BAR; PG8_SCHED;
;             PG8_LDB(B0, 1, 0); PG8_LDB(B1, 1, 1); PG8_SCHED; PG8_LDA(At, 1, 0); PG8_STAGE(PG8_SA(0, 1), a2 + hstep, voffA);
;             PG8_WAIT_V(8); PG8_WAIT_L(0); PG8_BAR; __builtin_amdgcn_s_setprio(1); PG8_MMA_NP(0, 0, At, B0); PG8_MMA_NP(0, 1, At, B1); __builtin_amdgcn_s_setprio(0); PG8_BAR; PG8_SCHED;
	s_setprio 1
	s_waitcnt lgkmcnt(0)
	v_mfma_f32_16x16x32_bf16 v[94:97], v[142:145], v[206:209], 0
	v_mfma_f32_16x16x32_bf16 v[90:93], v[150:153], v[206:209], 0
	v_mfma_f32_16x16x32_bf16 v[86:89], v[142:145], v[214:217], 0
	v_mfma_f32_16x16x32_bf16 v[82:85], v[150:153], v[214:217], 0
	v_mfma_f32_16x16x32_bf16 v[78:81], v[142:145], v[222:225], 0
	v_mfma_f32_16x16x32_bf16 v[74:77], v[150:153], v[222:225], 0
	v_mfma_f32_16x16x32_bf16 v[70:73], v[142:145], v[230:233], 0
	v_mfma_f32_16x16x32_bf16 v[66:69], v[150:153], v[230:233], 0
	v_mfma_f32_16x16x32_bf16 v[30:33], v[178:181], v[206:209], 0
	v_mfma_f32_16x16x32_bf16 v[26:29], v[186:189], v[206:209], 0
	v_mfma_f32_16x16x32_bf16 v[22:25], v[178:181], v[214:217], 0
	v_mfma_f32_16x16x32_bf16 v[18:21], v[186:189], v[214:217], 0
	v_mfma_f32_16x16x32_bf16 v[14:17], v[178:181], v[222:225], 0
	v_mfma_f32_16x16x32_bf16 v[10:13], v[186:189], v[222:225], 0
	v_mfma_f32_16x16x32_bf16 v[6:9], v[178:181], v[230:233], 0
	v_mfma_f32_16x16x32_bf16 v[2:5], v[186:189], v[230:233], 0
	v_mfma_f32_16x16x32_bf16 v[94:97], v[146:149], v[210:213], v[94:97]
	v_mfma_f32_16x16x32_bf16 v[90:93], v[154:157], v[210:213], v[90:93]
	v_mfma_f32_16x16x32_bf16 v[86:89], v[146:149], v[218:221], v[86:89]
	v_mfma_f32_16x16x32_bf16 v[82:85], v[154:157], v[218:221], v[82:85]
	v_mfma_f32_16x16x32_bf16 v[78:81], v[146:149], v[226:229], v[78:81]
	v_mfma_f32_16x16x32_bf16 v[74:77], v[154:157], v[226:229], v[74:77]
	v_mfma_f32_16x16x32_bf16 v[70:73], v[146:149], v[234:237], v[70:73]
	v_mfma_f32_16x16x32_bf16 v[66:69], v[154:157], v[234:237], v[66:69]
	v_mfma_f32_16x16x32_bf16 v[30:33], v[182:185], v[210:213], v[30:33]
	v_mfma_f32_16x16x32_bf16 v[26:29], v[202:205], v[210:213], v[26:29]
	v_mfma_f32_16x16x32_bf16 v[22:25], v[182:185], v[218:221], v[22:25]
	v_mfma_f32_16x16x32_bf16 v[18:21], v[202:205], v[218:221], v[18:21]
	v_mfma_f32_16x16x32_bf16 v[14:17], v[182:185], v[226:229], v[14:17]
	v_mfma_f32_16x16x32_bf16 v[10:13], v[202:205], v[226:229], v[10:13]
	v_mfma_f32_16x16x32_bf16 v[6:9], v[182:185], v[234:237], v[6:9]
	v_mfma_f32_16x16x32_bf16 v[2:5], v[202:205], v[234:237], v[2:5]
	s_setprio 0
	s_barrier
	s_add_i32 s22, 0, 0x18000
	s_add_i32 s23, 0, 0x1c000
	v_add_u32_e32 v154, s22, v159
	v_add_u32_e32 v202, s23, v159
	ds_read_b128 v[142:145], v154
	ds_read_b128 v[146:149], v154 offset:1024
	ds_read_b128 v[150:153], v154 offset:2048
	ds_read_b128 v[154:157], v154 offset:3072
	ds_read_b128 v[178:181], v202
	ds_read_b128 v[182:185], v202 offset:1024
	ds_read_b128 v[186:189], v202 offset:2048
	ds_read_b128 v[202:205], v202 offset:3072
	s_add_u32 s14, s14, 0x40000
	s_addc_u32 s15, s15, 0
	s_mov_b32 m0, s40
	v_lshl_add_u64 v[242:243], s[14:15], 0, v[134:135]
	ds_read_b128 v[206:209], v161 offset:32768
	ds_read_b128 v[210:213], v161 offset:33792
	ds_read_b128 v[214:217], v161 offset:34816
	ds_read_b128 v[218:221], v161 offset:35840
	ds_read_b128 v[222:225], v161 offset:36864
	ds_read_b128 v[226:229], v161 offset:37888
	ds_read_b128 v[230:233], v161 offset:38912
	ds_read_b128 v[234:237], v161 offset:39936
	global_load_lds_dwordx4 v[242:243], off
	v_lshl_add_u64 v[242:243], s[14:15], 0, v[132:133]
	s_mov_b32 m0, s41
	s_nop 0
	global_load_lds_dwordx4 v[242:243], off
	s_waitcnt vmcnt(8)
	s_waitcnt lgkmcnt(0)
	s_barrier
	s_setprio 1
	s_waitcnt lgkmcnt(0)
	v_mfma_f32_16x16x32_bf16 v[126:129], v[142:145], v[206:209], v[126:129]
	v_mfma_f32_16x16x32_bf16 v[122:125], v[150:153], v[206:209], v[122:125]
	v_mfma_f32_16x16x32_bf16 v[118:121], v[142:145], v[214:217], v[118:121]
	v_mfma_f32_16x16x32_bf16 v[114:117], v[150:153], v[214:217], v[114:117]
	v_mfma_f32_16x16x32_bf16 v[110:113], v[142:145], v[222:225], v[110:113]
	v_mfma_f32_16x16x32_bf16 v[106:109], v[150:153], v[222:225], v[106:109]
	v_mfma_f32_16x16x32_bf16 v[102:105], v[142:145], v[230:233], v[102:105]
	v_mfma_f32_16x16x32_bf16 v[98:101], v[150:153], v[230:233], v[98:101]
	v_mfma_f32_16x16x32_bf16 v[62:65], v[178:181], v[206:209], v[62:65]
	v_mfma_f32_16x16x32_bf16 v[58:61], v[186:189], v[206:209], v[58:61]
	v_mfma_f32_16x16x32_bf16 v[54:57], v[178:181], v[214:217], v[54:57]
	v_mfma_f32_16x16x32_bf16 v[50:53], v[186:189], v[214:217], v[50:53]
	v_mfma_f32_16x16x32_bf16 v[46:49], v[178:181], v[222:225], v[46:49]
	v_mfma_f32_16x16x32_bf16 v[42:45], v[186:189], v[222:225], v[42:45]
	v_mfma_f32_16x16x32_bf16 v[38:41], v[178:181], v[230:233], v[38:41]
	v_mfma_f32_16x16x32_bf16 v[34:37], v[186:189], v[230:233], v[34:37]
	v_mfma_f32_16x16x32_bf16 v[126:129], v[146:149], v[210:213], v[126:129]
	v_mfma_f32_16x16x32_bf16 v[122:125], v[154:157], v[210:213], v[122:125]
	v_mfma_f32_16x16x32_bf16 v[118:121], v[146:149], v[218:221], v[118:121]
	v_mfma_f32_16x16x32_bf16 v[114:117], v[154:157], v[218:221], v[114:117]
	v_mfma_f32_16x16x32_bf16 v[110:113], v[146:149], v[226:229], v[110:113]
	v_mfma_f32_16x16x32_bf16 v[106:109], v[154:157], v[226:229], v[106:109]
	v_mfma_f32_16x16x32_bf16 v[102:105], v[146:149], v[234:237], v[102:105]
	v_mfma_f32_16x16x32_bf16 v[98:101], v[154:157], v[234:237], v[98:101]
	v_mfma_f32_16x16x32_bf16 v[62:65], v[182:185], v[210:213], v[62:65]
	v_mfma_f32_16x16x32_bf16 v[58:61], v[202:205], v[210:213], v[58:61]
	v_mfma_f32_16x16x32_bf16 v[54:57], v[182:185], v[218:221], v[54:57]
	v_mfma_f32_16x16x32_bf16 v[50:53], v[202:205], v[218:221], v[50:53]
	v_mfma_f32_16x16x32_bf16 v[46:49], v[182:185], v[226:229], v[46:49]
	v_mfma_f32_16x16x32_bf16 v[42:45], v[202:205], v[226:229], v[42:45]
	v_mfma_f32_16x16x32_bf16 v[38:41], v[182:185], v[234:237], v[38:41]
	v_mfma_f32_16x16x32_bf16 v[34:37], v[202:205], v[234:237], v[34:37]
	s_setprio 0
	s_barrier
; #define PG8_STAGE(bufoff, gbase, voff) do { _Pragma("unroll") for (int _i = 0; _i < 2; ++_i) \
;         __builtin_amdgcn_global_load_lds((const unsigned*)((const char*)(gbase) + (voff)[_i]), (PG8_LAS unsigned*)(lds + (bufoff) + ldsw + _i * 8192), 16, 0, 0); } while (0)
; #define PG8_LDA(dst, b, h) do { _Pragma("unroll") for (int m = 0; m < 4; ++m) _Pragma("unroll") for (int k = 0; k < 2; ++k) dst[m][k] = *(const PG8_LAS bf16x8*)(lds + PG8_SA(b, h) + aoff + m * 2048 + k * 1024); } while (0)
; #define PG8_MMA_NP(ai, bj, At, Bt) do { _Pragma("unroll") for (int m = 0; m < 4; ++m) _Pragma("unroll") for (int n = 0; n < 2; ++n) _Pragma("unroll") for (int k = 0; k < 2; ++k) \
;         acc[ai][bj][m][n] = __builtin_amdgcn_mfma_f32_16x16x32_bf16(Bt[n][k], At[m][k], acc[ai][bj][m][n], 0, 0, 0); } while (0)
; #define PG8_WAIT_V(n) asm volatile("s_waitcnt vmcnt(" #n ")" ::: "memory")
; #define PG8_WAIT_L(n) asm volatile("s_waitcnt lgkmcnt(" #n ")" ::: "memory")
; #define PG8_BAR __builtin_amdgcn_s_barrier()
; #define PG8_SCHED __builtin_amdgcn_sched_barrier(0)
; template <class Epi, class Sched, bool ALIGN_EPI = false, bool SP2 = false>
; __device__ __forceinline__ void gemm_phase(PG8_LAS unsigned char* lds, const Gemm g, const Sched& S, const Epi& E) {
;     ...
;             PG8_WAIT_V(8); PG8_WAIT_L(0); PG8_BAR; __builtin_amdgcn_s_setprio(1); PG8_MMA_NP(0, 0, At, B0); PG8_MMA_NP(0, 1, At, B1); __builtin_amdgcn_s_setprio(0); PG8_BAR; PG8_SCHED;
;             PG8_LDA(At, 1, 1); PG8_STAGE(PG8_SB(1, 0), b3, voffB); PG8_STAGE(PG8_SB(1, 1), b3 + hstep, voffB); PG8_STAGE(PG8_SA(1, 0), a3, voffA);
;             PG8_WAIT_V(8); PG8_WAIT_L(0); PG8_BAR; __builtin_amdgcn_s_setprio(1); PG8_MMA_NP(1, 0, At, B0); PG8_MMA_NP(1, 1, At, B1); __builtin_amdgcn_s_setprio(0); PG8_BAR; PG8_SCHED;
	s_add_i32 s14, s22, s8
	v_lshl_add_u64 v[162:163], v[162:163], 0, s[20:21]
	s_mov_b32 m0, s14
	ds_read_b128 v[206:209], v161 offset:49152
	ds_read_b128 v[210:213], v161 offset:50176
	ds_read_b128 v[214:217], v161 offset:51200
	ds_read_b128 v[218:221], v161 offset:52224
	ds_read_b128 v[222:225], v161 offset:53248
	ds_read_b128 v[226:229], v161 offset:54272
	ds_read_b128 v[230:233], v161 offset:55296
	ds_read_b128 v[234:237], v161 offset:56320
	global_load_lds_dwordx4 v[162:163], off
	s_add_i32 m0, s14, 0x2000
	s_add_u32 s12, s12, 0x40080
	v_lshl_add_u64 v[162:163], v[190:191], 0, s[20:21]
	s_addc_u32 s13, s13, 0
	s_add_i32 s14, s23, s8
	global_load_lds_dwordx4 v[162:163], off
	v_lshl_add_u64 v[162:163], s[12:13], 0, v[0:1]
	s_mov_b32 m0, s14
	s_nop 0
	global_load_lds_dwordx4 v[162:163], off
	v_lshl_add_u64 v[162:163], s[12:13], 0, v[130:131]
	s_add_i32 m0, s14, 0x2000
	s_nop 0
	global_load_lds_dwordx4 v[162:163], off
	v_lshl_add_u64 v[162:163], v[238:239], 0, s[20:21]
	s_mov_b32 m0, s54
	s_nop 0
	global_load_lds_dwordx4 v[162:163], off
	v_lshl_add_u64 v[162:163], v[240:241], 0, s[20:21]
	s_mov_b32 m0, s55
	s_nop 0
	global_load_lds_dwordx4 v[162:163], off
	s_waitcnt vmcnt(8)
	s_waitcnt lgkmcnt(0)
	s_barrier
	s_setprio 1
	s_waitcnt lgkmcnt(0)
	v_mfma_f32_16x16x32_bf16 v[94:97], v[142:145], v[206:209], v[94:97]
	v_mfma_f32_16x16x32_bf16 v[90:93], v[150:153], v[206:209], v[90:93]
	v_mfma_f32_16x16x32_bf16 v[86:89], v[142:145], v[214:217], v[86:89]
	v_mfma_f32_16x16x32_bf16 v[82:85], v[150:153], v[214:217], v[82:85]
	v_mfma_f32_16x16x32_bf16 v[78:81], v[142:145], v[222:225], v[78:81]
	v_mfma_f32_16x16x32_bf16 v[74:77], v[150:153], v[222:225], v[74:77]
	v_mfma_f32_16x16x32_bf16 v[70:73], v[142:145], v[230:233], v[70:73]
	v_mfma_f32_16x16x32_bf16 v[66:69], v[150:153], v[230:233], v[66:69]
	v_mfma_f32_16x16x32_bf16 v[30:33], v[178:181], v[206:209], v[30:33]
	v_mfma_f32_16x16x32_bf16 v[26:29], v[186:189], v[206:209], v[26:29]
	v_mfma_f32_16x16x32_bf16 v[22:25], v[178:181], v[214:217], v[22:25]
	v_mfma_f32_16x16x32_bf16 v[18:21], v[186:189], v[214:217], v[18:21]
	v_mfma_f32_16x16x32_bf16 v[14:17], v[178:181], v[222:225], v[14:17]
	v_mfma_f32_16x16x32_bf16 v[10:13], v[186:189], v[222:225], v[10:13]
	v_mfma_f32_16x16x32_bf16 v[6:9], v[178:181], v[230:233], v[6:9]
	v_mfma_f32_16x16x32_bf16 v[2:5], v[186:189], v[230:233], v[2:5]
	v_mfma_f32_16x16x32_bf16 v[94:97], v[146:149], v[210:213], v[94:97]
	v_mfma_f32_16x16x32_bf16 v[90:93], v[154:157], v[210:213], v[90:93]
	v_mfma_f32_16x16x32_bf16 v[86:89], v[146:149], v[218:221], v[86:89]
	v_mfma_f32_16x16x32_bf16 v[82:85], v[154:157], v[218:221], v[82:85]
	v_mfma_f32_16x16x32_bf16 v[78:81], v[146:149], v[226:229], v[78:81]
	v_mfma_f32_16x16x32_bf16 v[74:77], v[154:157], v[226:229], v[74:77]
	v_mfma_f32_16x16x32_bf16 v[70:73], v[146:149], v[234:237], v[70:73]
	v_mfma_f32_16x16x32_bf16 v[66:69], v[154:157], v[234:237], v[66:69]
	v_mfma_f32_16x16x32_bf16 v[30:33], v[182:185], v[210:213], v[30:33]
	v_mfma_f32_16x16x32_bf16 v[26:29], v[202:205], v[210:213], v[26:29]
	v_mfma_f32_16x16x32_bf16 v[22:25], v[182:185], v[218:221], v[22:25]
	v_mfma_f32_16x16x32_bf16 v[18:21], v[202:205], v[218:221], v[18:21]
	v_mfma_f32_16x16x32_bf16 v[14:17], v[182:185], v[226:229], v[14:17]
	v_mfma_f32_16x16x32_bf16 v[10:13], v[202:205], v[226:229], v[10:13]
	v_mfma_f32_16x16x32_bf16 v[6:9], v[182:185], v[234:237], v[6:9]
	v_mfma_f32_16x16x32_bf16 v[2:5], v[202:205], v[234:237], v[2:5]
	s_setprio 0
	s_barrier
	s_add_i32 s63, s63, 2
	s_add_u32 s2, s2, 0x100
	s_addc_u32 s3, s3, 0
	s_add_u32 s61, s61, 0x100
	s_addc_u32 s62, s62, 0
	s_cmp_gt_u32 s63, 13
	s_cbranch_scc0 .LBB0_432
	s_branch .Lkexit_3

; #define PG8_BAR __builtin_amdgcn_s_barrier()
; template <class Epi, class Sched, bool ALIGN_EPI = false, bool SP2 = false>
; __device__ __forceinline__ void gemm_phase(PG8_LAS unsigned char* lds, const Gemm g, const Sched& S, const Epi& E) {
;     ...
;         if constexpr (ALIGN_EPI) { if (wr == 0) PG8_BAR; }
.Lkexit_3:
	s_and_b64 vcc, exec, s[44:45]
	s_cbranch_vccz .LBB0_435
	s_barrier

; #define PG8_STAGE(bufoff, gbase, voff) do { _Pragma("unroll") for (int _i = 0; _i < 2; ++_i) \
;         __builtin_amdgcn_global_load_lds((const unsigned*)((const char*)(gbase) + (voff)[_i]), (PG8_LAS unsigned*)(lds + (bufoff) + ldsw + _i * 8192), 16, 0, 0); } while (0)
; #define PG8_LDA(dst, b, h) do { _Pragma("unroll") for (int m = 0; m < 4; ++m) _Pragma("unroll") for (int k = 0; k < 2; ++k) dst[m][k] = *(const PG8_LAS bf16x8*)(lds + PG8_SA(b, h) + aoff + m * 2048 + k * 1024); } while (0)
; #define PG8_LDB(dst, b, h) do { _Pragma("unroll") for (int n = 0; n < 2; ++n) _Pragma("unroll") for (int k = 0; k < 2; ++k) dst[n][k] = *(const PG8_LAS bf16x8*)(lds + PG8_SB(b, h) + boff + n * 2048 + k * 1024); } while (0)
; #define PG8_MMA_NP(ai, bj, At, Bt) do { _Pragma("unroll") for (int m = 0; m < 4; ++m) _Pragma("unroll") for (int n = 0; n < 2; ++n) _Pragma("unroll") for (int k = 0; k < 2; ++k) \
;         acc[ai][bj][m][n] = __builtin_amdgcn_mfma_f32_16x16x32_bf16(Bt[n][k], At[m][k], acc[ai][bj][m][n], 0, 0, 0); } while (0)
; #define PG8_WAIT_V(n) asm volatile("s_waitcnt vmcnt(" #n ")" ::: "memory")
; #define PG8_BAR __builtin_amdgcn_s_barrier()
; template <class Epi, class Sched, bool ALIGN_EPI = false, bool SP2 = false>
; __device__ __forceinline__ void gemm_phase(PG8_LAS unsigned char* lds, const Gemm g, const Sched& S, const Epi& E) {
;     ...
;     Unit cur, nxt; int ui = 0;
;     if (!S.next(0, cur)) return;
;     f32x4 acc[2][2][4][2];
; #pragma unroll
;     for (int a = 0; a < 2; ++a)
; #pragma unroll
;         for (int b = 0; b < 2; ++b)
; #pragma unroll
;             for (int m = 0; m < 4; ++m)
; #pragma unroll
;                 for (int n = 0; n < 2; ++n) acc[a][b][m][n] = (f32x4){0.f, 0.f, 0.f, 0.f};
;     ...
;             PG8_LDB(B0, 0, 0); PG8_LDB(B1, 0, 1); PG8_SCHED; PG8_LDA(At, 0, 0); PG8_STAGE(PG8_SA(1, 1), a1 + hstep, voffA);
;             PG8_WAIT_V(8); PG8_WAIT_L(0); PG8_BAR; __builtin_amdgcn_s_setprio(1); PG8_MMA_NP(0, 0, At, B0); PG8_MMA_NP(0, 1, At, B1); __builtin_amdgcn_s_setprio(0); PG8_BAR; PG8_SCHED;
;             PG8_LDA(At, 0, 1); PG8_STAGE(PG8_SB(0, 0), b2, voffB); PG8_STAGE(PG8_SB(0, 1), b2 + hstep, voffB); PG8_STAGE(PG8_SA(0, 0), a2, voffA);
;             PG8_WAIT_V(8); PG8_WAIT_L(0); PG8_BAR; __builtin_amdgcn_s_setprio(1); PG8_MMA_NP(1, 0, At, B0); PG8_MMA_NP(1, 1, At, B1); __builtin_amdgcn_s_setprio(0); PG8_BAR; PG8_SCHED;
.LBB0_1015:
	s_ashr_i32 s51, s50, 31
	s_lshl_b64 s[14:15], s[50:51], 19
	s_add_u32 s52, s90, s14
	s_addc_u32 s53, s91, s15
	s_and_b64 s[14:15], s[44:45], exec
	s_cselect_b32 s29, s53, s13
	s_cselect_b32 s30, s52, s12
	s_ashr_i32 s49, s48, 31
	s_lshl_b64 s[14:15], s[48:49], 19
	s_add_u32 s54, s31, s14
	s_addc_u32 s55, s40, s15
	s_and_b64 s[14:15], s[44:45], exec
	s_cselect_b32 s49, s55, s39
	s_cselect_b32 s51, s54, s38
	s_add_u32 s12, s12, 0x40080
	s_addc_u32 s13, s13, 0
	s_add_u32 s64, s38, 0x100
	s_addc_u32 s65, s39, 0
	s_mov_b32 s66, -2
	s_waitcnt lgkmcnt(0)
	s_add_u32 s14, s12, 0xfffc0080
	s_addc_u32 s15, s13, -1
	s_add_i32 s22, 0, 0x10000
	s_cmp_eq_u32 s66, 12
	s_cselect_b32 s39, s29, s15
	s_cselect_b32 s38, s30, s14
	v_add_u32_e32 v144, s22, v147
	s_cselect_b32 s15, s49, s65
	s_cselect_b32 s14, s51, s64
	s_add_i32 s67, 0, 0x14000
	ds_read_b128 v[140:143], v144
	ds_read_b128 v[150:153], v144 offset:1024
	ds_read_b128 v[154:157], v144 offset:2048
	ds_read_b128 v[158:161], v144 offset:3072
	v_add_u32_e32 v144, s67, v147
	ds_read_b128 v[178:181], v144
	ds_read_b128 v[182:185], v144 offset:1024
	ds_read_b128 v[186:189], v144 offset:2048
	ds_read_b128 v[202:205], v144 offset:3072
	v_lshl_add_u64 v[144:145], s[12:13], 0, v[136:137]
	s_add_i32 m0, s56, 0xc000
	ds_read_b128 v[206:209], v149
	ds_read_b128 v[210:213], v149 offset:1024
	ds_read_b128 v[214:217], v149 offset:2048
	ds_read_b128 v[218:221], v149 offset:3072
	ds_read_b128 v[222:225], v149 offset:4096
	ds_read_b128 v[226:229], v149 offset:5120
	ds_read_b128 v[230:233], v149 offset:6144
	ds_read_b128 v[234:237], v149 offset:7168
	global_load_lds_dwordx4 v[144:145], off
	v_lshl_add_u64 v[144:145], s[12:13], 0, v[138:139]
	s_add_i32 m0, s56, 0xe000
	s_nop 0
	global_load_lds_dwordx4 v[144:145], off
	s_waitcnt vmcnt(8)
	s_waitcnt lgkmcnt(0)
	s_barrier
	s_setprio 1
	s_waitcnt lgkmcnt(0)
	v_mfma_f32_16x16x32_bf16 v[126:129], v[140:143], v[206:209], 0
	v_mfma_f32_16x16x32_bf16 v[122:125], v[154:157], v[206:209], 0
	v_mfma_f32_16x16x32_bf16 v[110:113], v[140:143], v[214:217], 0
	v_mfma_f32_16x16x32_bf16 v[106:109], v[154:157], v[214:217], 0
	v_mfma_f32_16x16x32_bf16 v[94:97], v[140:143], v[222:225], 0
	v_mfma_f32_16x16x32_bf16 v[90:93], v[154:157], v[222:225], 0
	v_mfma_f32_16x16x32_bf16 v[78:81], v[140:143], v[230:233], 0
	v_mfma_f32_16x16x32_bf16 v[74:77], v[154:157], v[230:233], 0
	v_mfma_f32_16x16x32_bf16 v[118:121], v[178:181], v[206:209], 0
	v_mfma_f32_16x16x32_bf16 v[114:117], v[186:189], v[206:209], 0
	v_mfma_f32_16x16x32_bf16 v[102:105], v[178:181], v[214:217], 0
	v_mfma_f32_16x16x32_bf16 v[98:101], v[186:189], v[214:217], 0
	v_mfma_f32_16x16x32_bf16 v[86:89], v[178:181], v[222:225], 0
	v_mfma_f32_16x16x32_bf16 v[82:85], v[186:189], v[222:225], 0
	v_mfma_f32_16x16x32_bf16 v[70:73], v[178:181], v[230:233], 0
	v_mfma_f32_16x16x32_bf16 v[66:69], v[186:189], v[230:233], 0
	v_mfma_f32_16x16x32_bf16 v[126:129], v[150:153], v[210:213], v[126:129]
	v_mfma_f32_16x16x32_bf16 v[122:125], v[158:161], v[210:213], v[122:125]
	v_mfma_f32_16x16x32_bf16 v[110:113], v[150:153], v[218:221], v[110:113]
	v_mfma_f32_16x16x32_bf16 v[106:109], v[158:161], v[218:221], v[106:109]
	v_mfma_f32_16x16x32_bf16 v[94:97], v[150:153], v[226:229], v[94:97]
	v_mfma_f32_16x16x32_bf16 v[90:93], v[158:161], v[226:229], v[90:93]
	v_mfma_f32_16x16x32_bf16 v[78:81], v[150:153], v[234:237], v[78:81]
	v_mfma_f32_16x16x32_bf16 v[74:77], v[158:161], v[234:237], v[74:77]
	v_mfma_f32_16x16x32_bf16 v[118:121], v[182:185], v[210:213], v[118:121]
	v_mfma_f32_16x16x32_bf16 v[114:117], v[202:205], v[210:213], v[114:117]
	v_mfma_f32_16x16x32_bf16 v[102:105], v[182:185], v[218:221], v[102:105]
	v_mfma_f32_16x16x32_bf16 v[98:101], v[202:205], v[218:221], v[98:101]
	v_mfma_f32_16x16x32_bf16 v[86:89], v[182:185], v[226:229], v[86:89]
	v_mfma_f32_16x16x32_bf16 v[82:85], v[202:205], v[226:229], v[82:85]
	v_mfma_f32_16x16x32_bf16 v[70:73], v[182:185], v[234:237], v[70:73]
	v_mfma_f32_16x16x32_bf16 v[66:69], v[202:205], v[234:237], v[66:69]
	s_setprio 0
	s_barrier
	s_add_i32 s22, s22, s41
	v_lshl_add_u64 v[144:145], s[14:15], 0, v[0:1]
	s_mov_b32 m0, s22
	ds_read_b128 v[206:209], v149 offset:16384
	ds_read_b128 v[210:213], v149 offset:17408
	ds_read_b128 v[214:217], v149 offset:18432
	ds_read_b128 v[218:221], v149 offset:19456
	ds_read_b128 v[222:225], v149 offset:20480
	ds_read_b128 v[226:229], v149 offset:21504
	ds_read_b128 v[230:233], v149 offset:22528
	ds_read_b128 v[234:237], v149 offset:23552
	global_load_lds_dwordx4 v[144:145], off
	s_add_i32 m0, s22, 0x2000
	s_add_u32 s22, s14, 0x40000
	v_lshl_add_u64 v[162:163], s[14:15], 0, v[130:131]
	s_addc_u32 s23, s15, 0
	s_add_i32 s67, s67, s41
	global_load_lds_dwordx4 v[162:163], off
	v_lshl_add_u64 v[190:191], s[22:23], 0, v[0:1]
	s_mov_b32 m0, s67
	v_lshl_add_u64 v[238:239], s[38:39], 0, v[132:133]
	global_load_lds_dwordx4 v[190:191], off
	v_lshl_add_u64 v[190:191], s[22:23], 0, v[130:131]
	s_add_i32 m0, s67, 0x2000
	s_nop 0
	global_load_lds_dwordx4 v[190:191], off
	v_lshl_add_u64 v[190:191], s[38:39], 0, v[134:135]
	s_mov_b32 m0, s56
	s_nop 0
	global_load_lds_dwordx4 v[190:191], off
	s_mov_b32 m0, s57
	s_nop 0
	global_load_lds_dwordx4 v[238:239], off
	s_waitcnt vmcnt(8)
	s_waitcnt lgkmcnt(0)
	s_barrier
; #define PG8_STAGE(bufoff, gbase, voff) do { _Pragma("unroll") for (int _i = 0; _i < 2; ++_i) \
;         __builtin_amdgcn_global_load_lds((const unsigned*)((const char*)(gbase) + (voff)[_i]), (PG8_LAS unsigned*)(lds + (bufoff) + ldsw + _i * 8192), 16, 0, 0); } while (0)
; #define PG8_LDA(dst, b, h) do { _Pragma("unroll") for (int m = 0; m < 4; ++m) _Pragma("unroll") for (int k = 0; k < 2; ++k) dst[m][k] = *(const PG8_LAS bf16x8*)(lds + PG8_SA(b, h) + aoff + m * 2048 + k * 1024); } while (0)
; #define PG8_LDB(dst, b, h) do { _Pragma("unroll") for (int n = 0; n < 2; ++n) _Pragma("unroll") for (int k = 0; k < 2; ++k) dst[n][k] = *(const PG8_LAS bf16x8*)(lds + PG8_SB(b, h) + boff + n * 2048 + k * 1024); } while (0)
; #define PG8_MMA_NP(ai, bj, At, Bt) do { _Pragma("unroll") for (int m = 0; m < 4; ++m) _Pragma("unroll") for (int n = 0; n < 2; ++n) _Pragma("unroll") for (int k = 0; k < 2; ++k) \
;         acc[ai][bj][m][n] = __builtin_amdgcn_mfma_f32_16x16x32_bf16(Bt[n][k], At[m][k], acc[ai][bj][m][n], 0, 0, 0); } while (0)
; #define PG8_WAIT_V(n) asm volatile("s_waitcnt vmcnt(" #n ")" ::: "memory")
; #define PG8_WAIT_L(n) asm volatile("s_waitcnt lgkmcnt(" #n ")" ::: "memory")
; #define PG8_BAR __builtin_amdgcn_s_barrier()
; #define PG8_SCHED __builtin_amdgcn_sched_barrier(0)
; template <class Epi, class Sched, bool ALIGN_EPI = false, bool SP2 = false>
; __device__ __forceinline__ void gemm_phase(PG8_LAS unsigned char* lds, const Gemm g, const Sched& S, const Epi& E) {
;     ...
;             PG8_WAIT_V(8); PG8_WAIT_L(0); PG8_BAR; __builtin_amdgcn_s_setprio(1); PG8_MMA_NP(0, 0, At, B0); PG8_MMA_NP(0, 1, At, B1); __builtin_amdgcn_s_setprio(0); PG8_BAR; PG8_SCHED;
;             PG8_LDA(At, 0, 1); PG8_STAGE(PG8_SB(0, 0), b2, voffB); PG8_STAGE(PG8_SB(0, 1), b2 + hstep, voffB); PG8_STAGE(PG8_SA(0, 0), a2, voffA);
;             PG8_WAIT_V(8); PG8_WAIT_L(0); PG8_BAR; __builtin_amdgcn_s_setprio(1); PG8_MMA_NP(1, 0, At, B0); PG8_MMA_NP(1, 1, At, B1); __builtin_amdgcn_s_setprio(0); PG8_BAR; PG8_SCHED;
;             PG8_LDB(B0, 1, 0); PG8_LDB(B1, 1, 1); PG8_SCHED; PG8_LDA(At, 1, 0); PG8_STAGE(PG8_SA(0, 1), a2 + hstep, voffA);
;             PG8_WAIT_V(8); PG8_WAIT_L(0); PG8_BAR; __builtin_amdgcn_s_setprio(1); PG8_MMA_NP(0, 0, At, B0); PG8_MMA_NP(0, 1, At, B1); __builtin_amdgcn_s_setprio(0); PG8_BAR; PG8_SCHED;
	s_setprio 1
	s_waitcnt lgkmcnt(0)
	v_mfma_f32_16x16x32_bf16 v[62:65], v[140:143], v[206:209], 0
	v_mfma_f32_16x16x32_bf16 v[58:61], v[154:157], v[206:209], 0
	v_mfma_f32_16x16x32_bf16 v[46:49], v[140:143], v[214:217], 0
	v_mfma_f32_16x16x32_bf16 v[42:45], v[154:157], v[214:217], 0
	v_mfma_f32_16x16x32_bf16 v[30:33], v[140:143], v[222:225], 0
	v_mfma_f32_16x16x32_bf16 v[26:29], v[154:157], v[222:225], 0
	v_mfma_f32_16x16x32_bf16 v[14:17], v[140:143], v[230:233], 0
	v_mfma_f32_16x16x32_bf16 v[10:13], v[154:157], v[230:233], 0
	v_mfma_f32_16x16x32_bf16 v[54:57], v[178:181], v[206:209], 0
	v_mfma_f32_16x16x32_bf16 v[50:53], v[186:189], v[206:209], 0
	v_mfma_f32_16x16x32_bf16 v[38:41], v[178:181], v[214:217], 0
	v_mfma_f32_16x16x32_bf16 v[34:37], v[186:189], v[214:217], 0
	v_mfma_f32_16x16x32_bf16 v[22:25], v[178:181], v[222:225], 0
	v_mfma_f32_16x16x32_bf16 v[18:21], v[186:189], v[222:225], 0
	v_mfma_f32_16x16x32_bf16 v[6:9], v[178:181], v[230:233], 0
	v_mfma_f32_16x16x32_bf16 v[2:5], v[186:189], v[230:233], 0
	v_mfma_f32_16x16x32_bf16 v[62:65], v[150:153], v[210:213], v[62:65]
	v_mfma_f32_16x16x32_bf16 v[58:61], v[158:161], v[210:213], v[58:61]
	v_mfma_f32_16x16x32_bf16 v[46:49], v[150:153], v[218:221], v[46:49]
	v_mfma_f32_16x16x32_bf16 v[42:45], v[158:161], v[218:221], v[42:45]
	v_mfma_f32_16x16x32_bf16 v[30:33], v[150:153], v[226:229], v[30:33]
	v_mfma_f32_16x16x32_bf16 v[26:29], v[158:161], v[226:229], v[26:29]
	v_mfma_f32_16x16x32_bf16 v[14:17], v[150:153], v[234:237], v[14:17]
	v_mfma_f32_16x16x32_bf16 v[10:13], v[158:161], v[234:237], v[10:13]
	v_mfma_f32_16x16x32_bf16 v[54:57], v[182:185], v[210:213], v[54:57]
	v_mfma_f32_16x16x32_bf16 v[50:53], v[202:205], v[210:213], v[50:53]
	v_mfma_f32_16x16x32_bf16 v[38:41], v[182:185], v[218:221], v[38:41]
	v_mfma_f32_16x16x32_bf16 v[34:37], v[202:205], v[218:221], v[34:37]
	v_mfma_f32_16x16x32_bf16 v[22:25], v[182:185], v[226:229], v[22:25]
	v_mfma_f32_16x16x32_bf16 v[18:21], v[202:205], v[226:229], v[18:21]
	v_mfma_f32_16x16x32_bf16 v[6:9], v[182:185], v[234:237], v[6:9]
	v_mfma_f32_16x16x32_bf16 v[2:5], v[202:205], v[234:237], v[2:5]
	s_setprio 0
	s_barrier
	s_add_i32 s67, 0, 0x18000
	s_add_i32 s68, 0, 0x1c000
	v_add_u32_e32 v158, s67, v147
	v_add_u32_e32 v202, s68, v147
	ds_read_b128 v[140:143], v158
	ds_read_b128 v[150:153], v158 offset:1024
	ds_read_b128 v[154:157], v158 offset:2048
	ds_read_b128 v[158:161], v158 offset:3072
	ds_read_b128 v[178:181], v202
	ds_read_b128 v[182:185], v202 offset:1024
	ds_read_b128 v[186:189], v202 offset:2048
	ds_read_b128 v[202:205], v202 offset:3072
	s_add_u32 s22, s38, 0x40000
	s_addc_u32 s23, s39, 0
	s_mov_b32 m0, s58
	v_lshl_add_u64 v[240:241], s[22:23], 0, v[134:135]
	ds_read_b128 v[206:209], v149 offset:32768
	ds_read_b128 v[210:213], v149 offset:33792
	ds_read_b128 v[214:217], v149 offset:34816
	ds_read_b128 v[218:221], v149 offset:35840
	ds_read_b128 v[222:225], v149 offset:36864
	ds_read_b128 v[226:229], v149 offset:37888
	ds_read_b128 v[230:233], v149 offset:38912
	ds_read_b128 v[234:237], v149 offset:39936
	global_load_lds_dwordx4 v[240:241], off
	v_lshl_add_u64 v[240:241], s[22:23], 0, v[132:133]
	s_mov_b32 m0, s59
	s_nop 0
	global_load_lds_dwordx4 v[240:241], off
	s_waitcnt vmcnt(8)
	s_waitcnt lgkmcnt(0)
	s_barrier
	s_setprio 1
	s_waitcnt lgkmcnt(0)
	v_mfma_f32_16x16x32_bf16 v[126:129], v[140:143], v[206:209], v[126:129]
	v_mfma_f32_16x16x32_bf16 v[122:125], v[154:157], v[206:209], v[122:125]
	v_mfma_f32_16x16x32_bf16 v[110:113], v[140:143], v[214:217], v[110:113]
	v_mfma_f32_16x16x32_bf16 v[106:109], v[154:157], v[214:217], v[106:109]
	v_mfma_f32_16x16x32_bf16 v[94:97], v[140:143], v[222:225], v[94:97]
	v_mfma_f32_16x16x32_bf16 v[90:93], v[154:157], v[222:225], v[90:93]
	v_mfma_f32_16x16x32_bf16 v[78:81], v[140:143], v[230:233], v[78:81]
	v_mfma_f32_16x16x32_bf16 v[74:77], v[154:157], v[230:233], v[74:77]
	v_mfma_f32_16x16x32_bf16 v[118:121], v[178:181], v[206:209], v[118:121]
	v_mfma_f32_16x16x32_bf16 v[114:117], v[186:189], v[206:209], v[114:117]
	v_mfma_f32_16x16x32_bf16 v[102:105], v[178:181], v[214:217], v[102:105]
	v_mfma_f32_16x16x32_bf16 v[98:101], v[186:189], v[214:217], v[98:101]
	v_mfma_f32_16x16x32_bf16 v[86:89], v[178:181], v[222:225], v[86:89]
	v_mfma_f32_16x16x32_bf16 v[82:85], v[186:189], v[222:225], v[82:85]
	v_mfma_f32_16x16x32_bf16 v[70:73], v[178:181], v[230:233], v[70:73]
	v_mfma_f32_16x16x32_bf16 v[66:69], v[186:189], v[230:233], v[66:69]
	v_mfma_f32_16x16x32_bf16 v[126:129], v[150:153], v[210:213], v[126:129]
	v_mfma_f32_16x16x32_bf16 v[122:125], v[158:161], v[210:213], v[122:125]
	v_mfma_f32_16x16x32_bf16 v[110:113], v[150:153], v[218:221], v[110:113]
	v_mfma_f32_16x16x32_bf16 v[106:109], v[158:161], v[218:221], v[106:109]
	v_mfma_f32_16x16x32_bf16 v[94:97], v[150:153], v[226:229], v[94:97]
	v_mfma_f32_16x16x32_bf16 v[90:93], v[158:161], v[226:229], v[90:93]
	v_mfma_f32_16x16x32_bf16 v[78:81], v[150:153], v[234:237], v[78:81]
	v_mfma_f32_16x16x32_bf16 v[74:77], v[158:161], v[234:237], v[74:77]
	v_mfma_f32_16x16x32_bf16 v[118:121], v[182:185], v[210:213], v[118:121]
	v_mfma_f32_16x16x32_bf16 v[114:117], v[202:205], v[210:213], v[114:117]
	v_mfma_f32_16x16x32_bf16 v[102:105], v[182:185], v[218:221], v[102:105]
	v_mfma_f32_16x16x32_bf16 v[98:101], v[202:205], v[218:221], v[98:101]
	v_mfma_f32_16x16x32_bf16 v[86:89], v[182:185], v[226:229], v[86:89]
	v_mfma_f32_16x16x32_bf16 v[82:85], v[202:205], v[226:229], v[82:85]
	v_mfma_f32_16x16x32_bf16 v[70:73], v[182:185], v[234:237], v[70:73]
	v_mfma_f32_16x16x32_bf16 v[66:69], v[202:205], v[234:237], v[66:69]
	s_setprio 0
	s_barrier
; #define PG8_STAGE(bufoff, gbase, voff) do { _Pragma("unroll") for (int _i = 0; _i < 2; ++_i) \
;         __builtin_amdgcn_global_load_lds((const unsigned*)((const char*)(gbase) + (voff)[_i]), (PG8_LAS unsigned*)(lds + (bufoff) + ldsw + _i * 8192), 16, 0, 0); } while (0)
; #define PG8_LDA(dst, b, h) do { _Pragma("unroll") for (int m = 0; m < 4; ++m) _Pragma("unroll") for (int k = 0; k < 2; ++k) dst[m][k] = *(const PG8_LAS bf16x8*)(lds + PG8_SA(b, h) + aoff + m * 2048 + k * 1024); } while (0)
; #define PG8_MMA_NP(ai, bj, At, Bt) do { _Pragma("unroll") for (int m = 0; m < 4; ++m) _Pragma("unroll") for (int n = 0; n < 2; ++n) _Pragma("unroll") for (int k = 0; k < 2; ++k) \
;         acc[ai][bj][m][n] = __builtin_amdgcn_mfma_f32_16x16x32_bf16(Bt[n][k], At[m][k], acc[ai][bj][m][n], 0, 0, 0); } while (0)
; #define PG8_WAIT_V(n) asm volatile("s_waitcnt vmcnt(" #n ")" ::: "memory")
; #define PG8_WAIT_L(n) asm volatile("s_waitcnt lgkmcnt(" #n ")" ::: "memory")
; #define PG8_BAR __builtin_amdgcn_s_barrier()
; #define PG8_SCHED __builtin_amdgcn_sched_barrier(0)
; template <class Epi, class Sched, bool ALIGN_EPI = false, bool SP2 = false>
; __device__ __forceinline__ void gemm_phase(PG8_LAS unsigned char* lds, const Gemm g, const Sched& S, const Epi& E) {
;     ...
;             PG8_WAIT_V(8); PG8_WAIT_L(0); PG8_BAR; __builtin_amdgcn_s_setprio(1); PG8_MMA_NP(0, 0, At, B0); PG8_MMA_NP(0, 1, At, B1); __builtin_amdgcn_s_setprio(0); PG8_BAR; PG8_SCHED;
;             PG8_LDA(At, 1, 1); PG8_STAGE(PG8_SB(1, 0), b3, voffB); PG8_STAGE(PG8_SB(1, 1), b3 + hstep, voffB); PG8_STAGE(PG8_SA(1, 0), a3, voffA);
;             PG8_WAIT_V(8); PG8_WAIT_L(0); PG8_BAR; __builtin_amdgcn_s_setprio(1); PG8_MMA_NP(1, 0, At, B0); PG8_MMA_NP(1, 1, At, B1); __builtin_amdgcn_s_setprio(0); PG8_BAR; PG8_SCHED;
	s_add_i32 s22, s67, s41
	v_lshl_add_u64 v[144:145], v[144:145], 0, s[20:21]
	s_mov_b32 m0, s22
	ds_read_b128 v[206:209], v149 offset:49152
	ds_read_b128 v[210:213], v149 offset:50176
	ds_read_b128 v[214:217], v149 offset:51200
	ds_read_b128 v[218:221], v149 offset:52224
	ds_read_b128 v[222:225], v149 offset:53248
	ds_read_b128 v[226:229], v149 offset:54272
	ds_read_b128 v[230:233], v149 offset:55296
	ds_read_b128 v[234:237], v149 offset:56320
	global_load_lds_dwordx4 v[144:145], off
	s_add_i32 m0, s22, 0x2000
	s_add_u32 s14, s14, 0x40080
	v_lshl_add_u64 v[144:145], v[162:163], 0, s[20:21]
	s_addc_u32 s15, s15, 0
	s_add_i32 s22, s68, s41
	global_load_lds_dwordx4 v[144:145], off
	v_lshl_add_u64 v[144:145], s[14:15], 0, v[0:1]
	s_mov_b32 m0, s22
	s_nop 0
	global_load_lds_dwordx4 v[144:145], off
	v_lshl_add_u64 v[144:145], s[14:15], 0, v[130:131]
	s_add_i32 m0, s22, 0x2000
	s_nop 0
	global_load_lds_dwordx4 v[144:145], off
	v_lshl_add_u64 v[144:145], v[190:191], 0, s[20:21]
	s_mov_b32 m0, s61
	s_nop 0
	global_load_lds_dwordx4 v[144:145], off
	v_lshl_add_u64 v[144:145], v[238:239], 0, s[20:21]
	s_mov_b32 m0, s62
	s_nop 0
	global_load_lds_dwordx4 v[144:145], off
	s_waitcnt vmcnt(8)
	s_waitcnt lgkmcnt(0)
	s_barrier
	s_setprio 1
	s_waitcnt lgkmcnt(0)
	v_mfma_f32_16x16x32_bf16 v[62:65], v[140:143], v[206:209], v[62:65]
	v_mfma_f32_16x16x32_bf16 v[58:61], v[154:157], v[206:209], v[58:61]
	v_mfma_f32_16x16x32_bf16 v[46:49], v[140:143], v[214:217], v[46:49]
	v_mfma_f32_16x16x32_bf16 v[42:45], v[154:157], v[214:217], v[42:45]
	v_mfma_f32_16x16x32_bf16 v[30:33], v[140:143], v[222:225], v[30:33]
	v_mfma_f32_16x16x32_bf16 v[26:29], v[154:157], v[222:225], v[26:29]
	v_mfma_f32_16x16x32_bf16 v[14:17], v[140:143], v[230:233], v[14:17]
	v_mfma_f32_16x16x32_bf16 v[10:13], v[154:157], v[230:233], v[10:13]
	v_mfma_f32_16x16x32_bf16 v[54:57], v[178:181], v[206:209], v[54:57]
	v_mfma_f32_16x16x32_bf16 v[50:53], v[186:189], v[206:209], v[50:53]
	v_mfma_f32_16x16x32_bf16 v[38:41], v[178:181], v[214:217], v[38:41]
	v_mfma_f32_16x16x32_bf16 v[34:37], v[186:189], v[214:217], v[34:37]
	v_mfma_f32_16x16x32_bf16 v[22:25], v[178:181], v[222:225], v[22:25]
	v_mfma_f32_16x16x32_bf16 v[18:21], v[186:189], v[222:225], v[18:21]
	v_mfma_f32_16x16x32_bf16 v[6:9], v[178:181], v[230:233], v[6:9]
	v_mfma_f32_16x16x32_bf16 v[2:5], v[186:189], v[230:233], v[2:5]
	v_mfma_f32_16x16x32_bf16 v[62:65], v[150:153], v[210:213], v[62:65]
	v_mfma_f32_16x16x32_bf16 v[58:61], v[158:161], v[210:213], v[58:61]
	v_mfma_f32_16x16x32_bf16 v[46:49], v[150:153], v[218:221], v[46:49]
	v_mfma_f32_16x16x32_bf16 v[42:45], v[158:161], v[218:221], v[42:45]
	v_mfma_f32_16x16x32_bf16 v[30:33], v[150:153], v[226:229], v[30:33]
	v_mfma_f32_16x16x32_bf16 v[26:29], v[158:161], v[226:229], v[26:29]
	v_mfma_f32_16x16x32_bf16 v[14:17], v[150:153], v[234:237], v[14:17]
	v_mfma_f32_16x16x32_bf16 v[10:13], v[158:161], v[234:237], v[10:13]
	v_mfma_f32_16x16x32_bf16 v[54:57], v[182:185], v[210:213], v[54:57]
	v_mfma_f32_16x16x32_bf16 v[50:53], v[202:205], v[210:213], v[50:53]
	v_mfma_f32_16x16x32_bf16 v[38:41], v[182:185], v[218:221], v[38:41]
	v_mfma_f32_16x16x32_bf16 v[34:37], v[202:205], v[218:221], v[34:37]
	v_mfma_f32_16x16x32_bf16 v[22:25], v[182:185], v[226:229], v[22:25]
	v_mfma_f32_16x16x32_bf16 v[18:21], v[202:205], v[226:229], v[18:21]
	v_mfma_f32_16x16x32_bf16 v[6:9], v[182:185], v[234:237], v[6:9]
	v_mfma_f32_16x16x32_bf16 v[2:5], v[202:205], v[234:237], v[2:5]
	s_setprio 0
	s_barrier
	s_add_i32 s66, s66, 2
	s_add_u32 s12, s12, 0x100
	s_addc_u32 s13, s13, 0
	s_add_u32 s64, s64, 0x100
	s_addc_u32 s65, s65, 0
	s_cmp_gt_u32 s66, 13
	s_cbranch_scc0 .LBB0_1016
	s_branch .Lkexit_4

; #define PG8_BAR __builtin_amdgcn_s_barrier()
; DI float bflo(unsigned w) { return __uint_as_float(w << 16); }
; DI float bfhi(unsigned w) { return __uint_as_float(w & 0xffff0000u); }
; template <class Epi, class Sched, bool ALIGN_EPI = false, bool SP2 = false>
; __device__ __forceinline__ void gemm_phase(PG8_LAS unsigned char* lds, const Gemm g, const Sched& S, const Epi& E) {
;     ...
;         if constexpr (ALIGN_EPI) { if (wr == 0) PG8_BAR; }
;     DI void operator()(const f32x4 (&acc)[2][2][4][2], const pg8::Unit& u, int wr, int wc, int fr, int fq) const {
;     ...
;                 for (int bj = 0; bj < 2; ++bj) {
;                     const size_t off = (size_t)row * DM + col0 + bj * 128;
;                     f32x4 b0, b1;
;                     if (base32) { b0 = *(const f32x4*)(base32 + off); b1 = *(const f32x4*)(base32 + off + 4); }
;                     else { const u32x4 bb = *(const u32x4*)(XB + off); b0 = (f32x4){bflo(bb.x), bfhi(bb.x), bflo(bb.y), bfhi(bb.y)}; b1 = (f32x4){bflo(bb.z), bfhi(bb.z), bflo(bb.w), bfhi(bb.w)}; }
.Lkexit_4:
	v_lshl_add_u32 v160, s10, 8, v146
	v_ashrrev_i32_e32 v161, 31, v160
	v_lshl_or_b32 v162, s8, 8, v148
	v_ashrrev_i32_e32 v163, 31, v162
	v_lshlrev_b64 v[160:161], 10, v[160:161]
	v_lshl_add_u64 v[160:161], v[160:161], 0, v[162:163]
	v_lshl_add_u64 v[160:161], v[160:161], 1, s[86:87]
	global_load_dwordx4 v[178:181], v[160:161], off
	global_load_dwordx4 v[182:185], v[160:161], off offset:256
	s_mov_b64 vcc, 0x8000
	v_lshl_add_u64 v[162:163], v[160:161], 0, vcc
	global_load_dwordx4 v[186:189], v[162:163], off
	global_load_dwordx4 v[202:205], v[162:163], off offset:256
	s_mov_b64 vcc, 0x10000
	v_lshl_add_u64 v[162:163], v[160:161], 0, vcc
	global_load_dwordx4 v[206:209], v[162:163], off
	global_load_dwordx4 v[210:213], v[162:163], off offset:256
	s_mov_b64 vcc, 0x18000
	v_lshl_add_u64 v[162:163], v[160:161], 0, vcc
	global_load_dwordx4 v[214:217], v[162:163], off
	global_load_dwordx4 v[218:221], v[162:163], off offset:256
	s_mov_b64 vcc, 0x40000
	v_lshl_add_u64 v[162:163], v[160:161], 0, vcc
	global_load_dwordx4 v[222:225], v[162:163], off
	global_load_dwordx4 v[226:229], v[162:163], off offset:256
	s_mov_b64 vcc, 0x48000
	v_lshl_add_u64 v[162:163], v[160:161], 0, vcc
	global_load_dwordx4 v[230:233], v[162:163], off
	global_load_dwordx4 v[234:237], v[162:163], off offset:256
	s_and_b64 vcc, exec, s[46:47]
	s_cbranch_vccz .LBB0_1019
	s_barrier

; #define PG8_STAGE(bufoff, gbase, voff) do { _Pragma("unroll") for (int _i = 0; _i < 2; ++_i) \
;         __builtin_amdgcn_global_load_lds((const unsigned*)((const char*)(gbase) + (voff)[_i]), (PG8_LAS unsigned*)(lds + (bufoff) + ldsw + _i * 8192), 16, 0, 0); } while (0)
; #define PG8_LDA(dst, b, h) do { _Pragma("unroll") for (int m = 0; m < 4; ++m) _Pragma("unroll") for (int k = 0; k < 2; ++k) dst[m][k] = *(const PG8_LAS bf16x8*)(lds + PG8_SA(b, h) + aoff + m * 2048 + k * 1024); } while (0)
; #define PG8_LDB(dst, b, h) do { _Pragma("unroll") for (int n = 0; n < 2; ++n) _Pragma("unroll") for (int k = 0; k < 2; ++k) dst[n][k] = *(const PG8_LAS bf16x8*)(lds + PG8_SB(b, h) + boff + n * 2048 + k * 1024); } while (0)
; #define PG8_MMA_NP(ai, bj, At, Bt) do { _Pragma("unroll") for (int m = 0; m < 4; ++m) _Pragma("unroll") for (int n = 0; n < 2; ++n) _Pragma("unroll") for (int k = 0; k < 2; ++k) \
;         acc[ai][bj][m][n] = __builtin_amdgcn_mfma_f32_16x16x32_bf16(Bt[n][k], At[m][k], acc[ai][bj][m][n], 0, 0, 0); } while (0)
; #define PG8_WAIT_V(n) asm volatile("s_waitcnt vmcnt(" #n ")" ::: "memory")
; #define PG8_BAR __builtin_amdgcn_s_barrier()
; template <class Epi, class Sched, bool ALIGN_EPI = false, bool SP2 = false>
; __device__ __forceinline__ void gemm_phase(PG8_LAS unsigned char* lds, const Gemm g, const Sched& S, const Epi& E) {
;     ...
;     Unit cur, nxt; int ui = 0;
;     if (!S.next(0, cur)) return;
;     f32x4 acc[2][2][4][2];
; #pragma unroll
;     for (int a = 0; a < 2; ++a)
; #pragma unroll
;         for (int b = 0; b < 2; ++b)
; #pragma unroll
;             for (int m = 0; m < 4; ++m)
; #pragma unroll
;                 for (int n = 0; n < 2; ++n) acc[a][b][m][n] = (f32x4){0.f, 0.f, 0.f, 0.f};
;     ...
;             PG8_LDB(B0, 0, 0); PG8_LDB(B1, 0, 1); PG8_SCHED; PG8_LDA(At, 0, 0); PG8_STAGE(PG8_SA(1, 1), a1 + hstep, voffA);
;             PG8_WAIT_V(8); PG8_WAIT_L(0); PG8_BAR; __builtin_amdgcn_s_setprio(1); PG8_MMA_NP(0, 0, At, B0); PG8_MMA_NP(0, 1, At, B1); __builtin_amdgcn_s_setprio(0); PG8_BAR; PG8_SCHED;
;             PG8_LDA(At, 0, 1); PG8_STAGE(PG8_SB(0, 0), b2, voffB); PG8_STAGE(PG8_SB(0, 1), b2 + hstep, voffB); PG8_STAGE(PG8_SA(0, 0), a2, voffA);
;             PG8_WAIT_V(8); PG8_WAIT_L(0); PG8_BAR; __builtin_amdgcn_s_setprio(1); PG8_MMA_NP(1, 0, At, B0); PG8_MMA_NP(1, 1, At, B1); __builtin_amdgcn_s_setprio(0); PG8_BAR; PG8_SCHED;
.LBB0_1121:
	s_ashr_i32 s49, s48, 31
	s_lshl_b64 s[14:15], s[48:49], 19
	s_add_u32 s50, s86, s14
	s_addc_u32 s51, s87, s15
	s_and_b64 s[14:15], s[38:39], exec
	s_cselect_b32 s49, s51, s3
	s_cselect_b32 s59, s50, s2
	s_ashr_i32 s47, s46, 31
	s_lshl_b64 s[14:15], s[46:47], 19
	s_add_u32 s52, s8, s14
	s_addc_u32 s53, s10, s15
	s_and_b64 s[14:15], s[38:39], exec
	s_cselect_b32 s47, s53, s13
	s_cselect_b32 s60, s52, s12
	s_add_u32 s2, s2, 0x40080
	s_addc_u32 s3, s3, 0
	s_add_u32 s61, s12, 0x100
	s_addc_u32 s62, s13, 0
	s_mov_b32 s63, -2
	s_add_u32 s12, s2, 0xfffc0080
	s_addc_u32 s13, s3, -1
	s_add_i32 s22, 0, 0x10000
	s_cmp_eq_u32 s63, 12
	s_cselect_b32 s15, s49, s13
	s_cselect_b32 s14, s59, s12
	s_cselect_b32 s13, s47, s62
	s_cselect_b32 s12, s60, s61
	s_add_i32 s64, 0, 0x14000
	v_add_u32_e32 v154, s22, v183
	v_add_u32_e32 v162, s64, v183
	ds_read_b128 v[130:133], v154
	ds_read_b128 v[146:149], v154 offset:1024
	ds_read_b128 v[150:153], v154 offset:2048
	ds_read_b128 v[154:157], v154 offset:3072
	ds_read_b128 v[158:161], v162
	ds_read_b128 v[178:181], v162 offset:1024
	ds_read_b128 v[186:189], v162 offset:2048
	ds_read_b128 v[202:205], v162 offset:3072
	v_lshl_add_u64 v[162:163], s[2:3], 0, v[142:143]
	s_add_i32 m0, s30, 0xc000
	ds_read_b128 v[206:209], v185
	ds_read_b128 v[210:213], v185 offset:1024
	ds_read_b128 v[214:217], v185 offset:2048
	ds_read_b128 v[218:221], v185 offset:3072
	ds_read_b128 v[222:225], v185 offset:4096
	ds_read_b128 v[226:229], v185 offset:5120
	ds_read_b128 v[230:233], v185 offset:6144
	ds_read_b128 v[234:237], v185 offset:7168
	global_load_lds_dwordx4 v[162:163], off
	v_lshl_add_u64 v[162:163], s[2:3], 0, v[144:145]
	s_add_i32 m0, s30, 0xe000
	s_nop 0
	global_load_lds_dwordx4 v[162:163], off
	s_waitcnt vmcnt(8)
	s_waitcnt lgkmcnt(0)
	s_barrier
	s_setprio 1
	s_waitcnt lgkmcnt(0)
	v_mfma_f32_16x16x32_bf16 v[126:129], v[130:133], v[206:209], 0
	v_mfma_f32_16x16x32_bf16 v[118:121], v[150:153], v[206:209], 0
	v_mfma_f32_16x16x32_bf16 v[110:113], v[130:133], v[214:217], 0
	v_mfma_f32_16x16x32_bf16 v[102:105], v[150:153], v[214:217], 0
	v_mfma_f32_16x16x32_bf16 v[94:97], v[130:133], v[222:225], 0
	v_mfma_f32_16x16x32_bf16 v[86:89], v[150:153], v[222:225], 0
	v_mfma_f32_16x16x32_bf16 v[78:81], v[130:133], v[230:233], 0
	v_mfma_f32_16x16x32_bf16 v[70:73], v[150:153], v[230:233], 0
	v_mfma_f32_16x16x32_bf16 v[122:125], v[158:161], v[206:209], 0
	v_mfma_f32_16x16x32_bf16 v[114:117], v[186:189], v[206:209], 0
	v_mfma_f32_16x16x32_bf16 v[106:109], v[158:161], v[214:217], 0
	v_mfma_f32_16x16x32_bf16 v[98:101], v[186:189], v[214:217], 0
	v_mfma_f32_16x16x32_bf16 v[90:93], v[158:161], v[222:225], 0
	v_mfma_f32_16x16x32_bf16 v[82:85], v[186:189], v[222:225], 0
	v_mfma_f32_16x16x32_bf16 v[74:77], v[158:161], v[230:233], 0
	v_mfma_f32_16x16x32_bf16 v[66:69], v[186:189], v[230:233], 0
	v_mfma_f32_16x16x32_bf16 v[126:129], v[146:149], v[210:213], v[126:129]
	v_mfma_f32_16x16x32_bf16 v[118:121], v[154:157], v[210:213], v[118:121]
	v_mfma_f32_16x16x32_bf16 v[110:113], v[146:149], v[218:221], v[110:113]
	v_mfma_f32_16x16x32_bf16 v[102:105], v[154:157], v[218:221], v[102:105]
	v_mfma_f32_16x16x32_bf16 v[94:97], v[146:149], v[226:229], v[94:97]
	v_mfma_f32_16x16x32_bf16 v[86:89], v[154:157], v[226:229], v[86:89]
	v_mfma_f32_16x16x32_bf16 v[78:81], v[146:149], v[234:237], v[78:81]
	v_mfma_f32_16x16x32_bf16 v[70:73], v[154:157], v[234:237], v[70:73]
	v_mfma_f32_16x16x32_bf16 v[122:125], v[178:181], v[210:213], v[122:125]
	v_mfma_f32_16x16x32_bf16 v[114:117], v[202:205], v[210:213], v[114:117]
	v_mfma_f32_16x16x32_bf16 v[106:109], v[178:181], v[218:221], v[106:109]
	v_mfma_f32_16x16x32_bf16 v[98:101], v[202:205], v[218:221], v[98:101]
	v_mfma_f32_16x16x32_bf16 v[90:93], v[178:181], v[226:229], v[90:93]
	v_mfma_f32_16x16x32_bf16 v[82:85], v[202:205], v[226:229], v[82:85]
	v_mfma_f32_16x16x32_bf16 v[74:77], v[178:181], v[234:237], v[74:77]
	v_mfma_f32_16x16x32_bf16 v[66:69], v[202:205], v[234:237], v[66:69]
	s_setprio 0
	s_barrier
	s_add_i32 s22, s22, s29
	v_lshl_add_u64 v[162:163], s[12:13], 0, v[0:1]
	s_mov_b32 m0, s22
	ds_read_b128 v[206:209], v185 offset:16384
	ds_read_b128 v[210:213], v185 offset:17408
	ds_read_b128 v[214:217], v185 offset:18432
	ds_read_b128 v[218:221], v185 offset:19456
	ds_read_b128 v[222:225], v185 offset:20480
	ds_read_b128 v[226:229], v185 offset:21504
	ds_read_b128 v[230:233], v185 offset:22528
	ds_read_b128 v[234:237], v185 offset:23552
	global_load_lds_dwordx4 v[162:163], off
	s_add_i32 m0, s22, 0x2000
	s_add_u32 s22, s12, 0x40000
	v_lshl_add_u64 v[190:191], s[12:13], 0, v[134:135]
	s_addc_u32 s23, s13, 0
	s_add_i32 s64, s64, s29
	global_load_lds_dwordx4 v[190:191], off
	v_lshl_add_u64 v[238:239], s[22:23], 0, v[0:1]
	s_mov_b32 m0, s64
	v_lshl_add_u64 v[240:241], s[14:15], 0, v[136:137]
	global_load_lds_dwordx4 v[238:239], off
	v_lshl_add_u64 v[238:239], s[22:23], 0, v[134:135]
	s_add_i32 m0, s64, 0x2000
	s_nop 0
	global_load_lds_dwordx4 v[238:239], off
	v_lshl_add_u64 v[238:239], s[14:15], 0, v[138:139]
	s_mov_b32 m0, s30
	s_nop 0
	global_load_lds_dwordx4 v[238:239], off
	s_mov_b32 m0, s31
	s_nop 0
	global_load_lds_dwordx4 v[240:241], off
	s_waitcnt vmcnt(8)
	s_waitcnt lgkmcnt(0)
	s_barrier
; #define PG8_STAGE(bufoff, gbase, voff) do { _Pragma("unroll") for (int _i = 0; _i < 2; ++_i) \
;         __builtin_amdgcn_global_load_lds((const unsigned*)((const char*)(gbase) + (voff)[_i]), (PG8_LAS unsigned*)(lds + (bufoff) + ldsw + _i * 8192), 16, 0, 0); } while (0)
; #define PG8_LDA(dst, b, h) do { _Pragma("unroll") for (int m = 0; m < 4; ++m) _Pragma("unroll") for (int k = 0; k < 2; ++k) dst[m][k] = *(const PG8_LAS bf16x8*)(lds + PG8_SA(b, h) + aoff + m * 2048 + k * 1024); } while (0)
; #define PG8_LDB(dst, b, h) do { _Pragma("unroll") for (int n = 0; n < 2; ++n) _Pragma("unroll") for (int k = 0; k < 2; ++k) dst[n][k] = *(const PG8_LAS bf16x8*)(lds + PG8_SB(b, h) + boff + n * 2048 + k * 1024); } while (0)
; #define PG8_MMA_NP(ai, bj, At, Bt) do { _Pragma("unroll") for (int m = 0; m < 4; ++m) _Pragma("unroll") for (int n = 0; n < 2; ++n) _Pragma("unroll") for (int k = 0; k < 2; ++k) \
;         acc[ai][bj][m][n] = __builtin_amdgcn_mfma_f32_16x16x32_bf16(Bt[n][k], At[m][k], acc[ai][bj][m][n], 0, 0, 0); } while (0)
; #define PG8_WAIT_V(n) asm volatile("s_waitcnt vmcnt(" #n ")" ::: "memory")
; #define PG8_WAIT_L(n) asm volatile("s_waitcnt lgkmcnt(" #n ")" ::: "memory")
; #define PG8_BAR __builtin_amdgcn_s_barrier()
; #define PG8_SCHED __builtin_amdgcn_sched_barrier(0)
; template <class Epi, class Sched, bool ALIGN_EPI = false, bool SP2 = false>
; __device__ __forceinline__ void gemm_phase(PG8_LAS unsigned char* lds, const Gemm g, const Sched& S, const Epi& E) {
;     ...
;             PG8_WAIT_V(8); PG8_WAIT_L(0); PG8_BAR; __builtin_amdgcn_s_setprio(1); PG8_MMA_NP(0, 0, At, B0); PG8_MMA_NP(0, 1, At, B1); __builtin_amdgcn_s_setprio(0); PG8_BAR; PG8_SCHED;
;             PG8_LDA(At, 0, 1); PG8_STAGE(PG8_SB(0, 0), b2, voffB); PG8_STAGE(PG8_SB(0, 1), b2 + hstep, voffB); PG8_STAGE(PG8_SA(0, 0), a2, voffA);
;             PG8_WAIT_V(8); PG8_WAIT_L(0); PG8_BAR; __builtin_amdgcn_s_setprio(1); PG8_MMA_NP(1, 0, At, B0); PG8_MMA_NP(1, 1, At, B1); __builtin_amdgcn_s_setprio(0); PG8_BAR; PG8_SCHED;
;             PG8_LDB(B0, 1, 0); PG8_LDB(B1, 1, 1); PG8_SCHED; PG8_LDA(At, 1, 0); PG8_STAGE(PG8_SA(0, 1), a2 + hstep, voffA);
;             PG8_WAIT_V(8); PG8_WAIT_L(0); PG8_BAR; __builtin_amdgcn_s_setprio(1); PG8_MMA_NP(0, 0, At, B0); PG8_MMA_NP(0, 1, At, B1); __builtin_amdgcn_s_setprio(0); PG8_BAR; PG8_SCHED;
	s_setprio 1
	s_waitcnt lgkmcnt(0)
	v_mfma_f32_16x16x32_bf16 v[62:65], v[130:133], v[206:209], 0
	v_mfma_f32_16x16x32_bf16 v[54:57], v[150:153], v[206:209], 0
	v_mfma_f32_16x16x32_bf16 v[46:49], v[130:133], v[214:217], 0
	v_mfma_f32_16x16x32_bf16 v[38:41], v[150:153], v[214:217], 0
	v_mfma_f32_16x16x32_bf16 v[30:33], v[130:133], v[222:225], 0
	v_mfma_f32_16x16x32_bf16 v[22:25], v[150:153], v[222:225], 0
	v_mfma_f32_16x16x32_bf16 v[14:17], v[130:133], v[230:233], 0
	v_mfma_f32_16x16x32_bf16 v[6:9], v[150:153], v[230:233], 0
	v_mfma_f32_16x16x32_bf16 v[58:61], v[158:161], v[206:209], 0
	v_mfma_f32_16x16x32_bf16 v[50:53], v[186:189], v[206:209], 0
	v_mfma_f32_16x16x32_bf16 v[42:45], v[158:161], v[214:217], 0
	v_mfma_f32_16x16x32_bf16 v[34:37], v[186:189], v[214:217], 0
	v_mfma_f32_16x16x32_bf16 v[26:29], v[158:161], v[222:225], 0
	v_mfma_f32_16x16x32_bf16 v[18:21], v[186:189], v[222:225], 0
	v_mfma_f32_16x16x32_bf16 v[10:13], v[158:161], v[230:233], 0
	v_mfma_f32_16x16x32_bf16 v[2:5], v[186:189], v[230:233], 0
	v_mfma_f32_16x16x32_bf16 v[62:65], v[146:149], v[210:213], v[62:65]
	v_mfma_f32_16x16x32_bf16 v[54:57], v[154:157], v[210:213], v[54:57]
	v_mfma_f32_16x16x32_bf16 v[46:49], v[146:149], v[218:221], v[46:49]
	v_mfma_f32_16x16x32_bf16 v[38:41], v[154:157], v[218:221], v[38:41]
	v_mfma_f32_16x16x32_bf16 v[30:33], v[146:149], v[226:229], v[30:33]
	v_mfma_f32_16x16x32_bf16 v[22:25], v[154:157], v[226:229], v[22:25]
	v_mfma_f32_16x16x32_bf16 v[14:17], v[146:149], v[234:237], v[14:17]
	v_mfma_f32_16x16x32_bf16 v[6:9], v[154:157], v[234:237], v[6:9]
	v_mfma_f32_16x16x32_bf16 v[58:61], v[178:181], v[210:213], v[58:61]
	v_mfma_f32_16x16x32_bf16 v[50:53], v[202:205], v[210:213], v[50:53]
	v_mfma_f32_16x16x32_bf16 v[42:45], v[178:181], v[218:221], v[42:45]
	v_mfma_f32_16x16x32_bf16 v[34:37], v[202:205], v[218:221], v[34:37]
	v_mfma_f32_16x16x32_bf16 v[26:29], v[178:181], v[226:229], v[26:29]
	v_mfma_f32_16x16x32_bf16 v[18:21], v[202:205], v[226:229], v[18:21]
	v_mfma_f32_16x16x32_bf16 v[10:13], v[178:181], v[234:237], v[10:13]
	v_mfma_f32_16x16x32_bf16 v[2:5], v[202:205], v[234:237], v[2:5]
	s_setprio 0
	s_barrier
	s_add_i32 s22, 0, 0x18000
	s_add_i32 s23, 0, 0x1c000
	v_add_u32_e32 v154, s22, v183
	v_add_u32_e32 v202, s23, v183
	ds_read_b128 v[130:133], v154
	ds_read_b128 v[146:149], v154 offset:1024
	ds_read_b128 v[150:153], v154 offset:2048
	ds_read_b128 v[154:157], v154 offset:3072
	ds_read_b128 v[158:161], v202
	ds_read_b128 v[178:181], v202 offset:1024
	ds_read_b128 v[186:189], v202 offset:2048
	ds_read_b128 v[202:205], v202 offset:3072
	s_add_u32 s14, s14, 0x40000
	s_addc_u32 s15, s15, 0
	s_mov_b32 m0, s40
	v_lshl_add_u64 v[242:243], s[14:15], 0, v[138:139]
	ds_read_b128 v[206:209], v185 offset:32768
	ds_read_b128 v[210:213], v185 offset:33792
	ds_read_b128 v[214:217], v185 offset:34816
	ds_read_b128 v[218:221], v185 offset:35840
	ds_read_b128 v[222:225], v185 offset:36864
	ds_read_b128 v[226:229], v185 offset:37888
	ds_read_b128 v[230:233], v185 offset:38912
	ds_read_b128 v[234:237], v185 offset:39936
	global_load_lds_dwordx4 v[242:243], off
	v_lshl_add_u64 v[242:243], s[14:15], 0, v[136:137]
	s_mov_b32 m0, s41
	s_nop 0
	global_load_lds_dwordx4 v[242:243], off
	s_waitcnt vmcnt(8)
	s_waitcnt lgkmcnt(0)
	s_barrier
	s_setprio 1
	s_waitcnt lgkmcnt(0)
	v_mfma_f32_16x16x32_bf16 v[126:129], v[130:133], v[206:209], v[126:129]
	v_mfma_f32_16x16x32_bf16 v[118:121], v[150:153], v[206:209], v[118:121]
	v_mfma_f32_16x16x32_bf16 v[110:113], v[130:133], v[214:217], v[110:113]
	v_mfma_f32_16x16x32_bf16 v[102:105], v[150:153], v[214:217], v[102:105]
	v_mfma_f32_16x16x32_bf16 v[94:97], v[130:133], v[222:225], v[94:97]
	v_mfma_f32_16x16x32_bf16 v[86:89], v[150:153], v[222:225], v[86:89]
	v_mfma_f32_16x16x32_bf16 v[78:81], v[130:133], v[230:233], v[78:81]
	v_mfma_f32_16x16x32_bf16 v[70:73], v[150:153], v[230:233], v[70:73]
	v_mfma_f32_16x16x32_bf16 v[122:125], v[158:161], v[206:209], v[122:125]
	v_mfma_f32_16x16x32_bf16 v[114:117], v[186:189], v[206:209], v[114:117]
	v_mfma_f32_16x16x32_bf16 v[106:109], v[158:161], v[214:217], v[106:109]
	v_mfma_f32_16x16x32_bf16 v[98:101], v[186:189], v[214:217], v[98:101]
	v_mfma_f32_16x16x32_bf16 v[90:93], v[158:161], v[222:225], v[90:93]
	v_mfma_f32_16x16x32_bf16 v[82:85], v[186:189], v[222:225], v[82:85]
	v_mfma_f32_16x16x32_bf16 v[74:77], v[158:161], v[230:233], v[74:77]
	v_mfma_f32_16x16x32_bf16 v[66:69], v[186:189], v[230:233], v[66:69]
	v_mfma_f32_16x16x32_bf16 v[126:129], v[146:149], v[210:213], v[126:129]
	v_mfma_f32_16x16x32_bf16 v[118:121], v[154:157], v[210:213], v[118:121]
	v_mfma_f32_16x16x32_bf16 v[110:113], v[146:149], v[218:221], v[110:113]
	v_mfma_f32_16x16x32_bf16 v[102:105], v[154:157], v[218:221], v[102:105]
	v_mfma_f32_16x16x32_bf16 v[94:97], v[146:149], v[226:229], v[94:97]
	v_mfma_f32_16x16x32_bf16 v[86:89], v[154:157], v[226:229], v[86:89]
	v_mfma_f32_16x16x32_bf16 v[78:81], v[146:149], v[234:237], v[78:81]
	v_mfma_f32_16x16x32_bf16 v[70:73], v[154:157], v[234:237], v[70:73]
	v_mfma_f32_16x16x32_bf16 v[122:125], v[178:181], v[210:213], v[122:125]
	v_mfma_f32_16x16x32_bf16 v[114:117], v[202:205], v[210:213], v[114:117]
	v_mfma_f32_16x16x32_bf16 v[106:109], v[178:181], v[218:221], v[106:109]
	v_mfma_f32_16x16x32_bf16 v[98:101], v[202:205], v[218:221], v[98:101]
	v_mfma_f32_16x16x32_bf16 v[90:93], v[178:181], v[226:229], v[90:93]
	v_mfma_f32_16x16x32_bf16 v[82:85], v[202:205], v[226:229], v[82:85]
	v_mfma_f32_16x16x32_bf16 v[74:77], v[178:181], v[234:237], v[74:77]
	v_mfma_f32_16x16x32_bf16 v[66:69], v[202:205], v[234:237], v[66:69]
	s_setprio 0
	s_barrier
; #define PG8_STAGE(bufoff, gbase, voff) do { _Pragma("unroll") for (int _i = 0; _i < 2; ++_i) \
;         __builtin_amdgcn_global_load_lds((const unsigned*)((const char*)(gbase) + (voff)[_i]), (PG8_LAS unsigned*)(lds + (bufoff) + ldsw + _i * 8192), 16, 0, 0); } while (0)
; #define PG8_LDA(dst, b, h) do { _Pragma("unroll") for (int m = 0; m < 4; ++m) _Pragma("unroll") for (int k = 0; k < 2; ++k) dst[m][k] = *(const PG8_LAS bf16x8*)(lds + PG8_SA(b, h) + aoff + m * 2048 + k * 1024); } while (0)
; #define PG8_MMA_NP(ai, bj, At, Bt) do { _Pragma("unroll") for (int m = 0; m < 4; ++m) _Pragma("unroll") for (int n = 0; n < 2; ++n) _Pragma("unroll") for (int k = 0; k < 2; ++k) \
;         acc[ai][bj][m][n] = __builtin_amdgcn_mfma_f32_16x16x32_bf16(Bt[n][k], At[m][k], acc[ai][bj][m][n], 0, 0, 0); } while (0)
; #define PG8_WAIT_V(n) asm volatile("s_waitcnt vmcnt(" #n ")" ::: "memory")
; #define PG8_WAIT_L(n) asm volatile("s_waitcnt lgkmcnt(" #n ")" ::: "memory")
; #define PG8_BAR __builtin_amdgcn_s_barrier()
; #define PG8_SCHED __builtin_amdgcn_sched_barrier(0)
; template <class Epi, class Sched, bool ALIGN_EPI = false, bool SP2 = false>
; __device__ __forceinline__ void gemm_phase(PG8_LAS unsigned char* lds, const Gemm g, const Sched& S, const Epi& E) {
;     ...
;             PG8_WAIT_V(8); PG8_WAIT_L(0); PG8_BAR; __builtin_amdgcn_s_setprio(1); PG8_MMA_NP(0, 0, At, B0); PG8_MMA_NP(0, 1, At, B1); __builtin_amdgcn_s_setprio(0); PG8_BAR; PG8_SCHED;
;             PG8_LDA(At, 1, 1); PG8_STAGE(PG8_SB(1, 0), b3, voffB); PG8_STAGE(PG8_SB(1, 1), b3 + hstep, voffB); PG8_STAGE(PG8_SA(1, 0), a3, voffA);
;             PG8_WAIT_V(8); PG8_WAIT_L(0); PG8_BAR; __builtin_amdgcn_s_setprio(1); PG8_MMA_NP(1, 0, At, B0); PG8_MMA_NP(1, 1, At, B1); __builtin_amdgcn_s_setprio(0); PG8_BAR; PG8_SCHED;
	s_add_i32 s14, s22, s29
	v_lshl_add_u64 v[162:163], v[162:163], 0, s[20:21]
	s_mov_b32 m0, s14
	ds_read_b128 v[206:209], v185 offset:49152
	ds_read_b128 v[210:213], v185 offset:50176
	ds_read_b128 v[214:217], v185 offset:51200
	ds_read_b128 v[218:221], v185 offset:52224
	ds_read_b128 v[222:225], v185 offset:53248
	ds_read_b128 v[226:229], v185 offset:54272
	ds_read_b128 v[230:233], v185 offset:55296
	ds_read_b128 v[234:237], v185 offset:56320
	global_load_lds_dwordx4 v[162:163], off
	s_add_i32 m0, s14, 0x2000
	s_add_u32 s12, s12, 0x40080
	v_lshl_add_u64 v[162:163], v[190:191], 0, s[20:21]
	s_addc_u32 s13, s13, 0
	s_add_i32 s14, s23, s29
	global_load_lds_dwordx4 v[162:163], off
	v_lshl_add_u64 v[162:163], s[12:13], 0, v[0:1]
	s_mov_b32 m0, s14
	s_nop 0
	global_load_lds_dwordx4 v[162:163], off
	v_lshl_add_u64 v[162:163], s[12:13], 0, v[134:135]
	s_add_i32 m0, s14, 0x2000
	s_nop 0
	global_load_lds_dwordx4 v[162:163], off
	v_lshl_add_u64 v[162:163], v[238:239], 0, s[20:21]
	s_mov_b32 m0, s54
	s_nop 0
	global_load_lds_dwordx4 v[162:163], off
	v_lshl_add_u64 v[162:163], v[240:241], 0, s[20:21]
	s_mov_b32 m0, s55
	s_nop 0
	global_load_lds_dwordx4 v[162:163], off
	s_waitcnt vmcnt(8)
	s_waitcnt lgkmcnt(0)
	s_barrier
	s_setprio 1
	s_waitcnt lgkmcnt(0)
	v_mfma_f32_16x16x32_bf16 v[62:65], v[130:133], v[206:209], v[62:65]
	v_mfma_f32_16x16x32_bf16 v[54:57], v[150:153], v[206:209], v[54:57]
	v_mfma_f32_16x16x32_bf16 v[46:49], v[130:133], v[214:217], v[46:49]
	v_mfma_f32_16x16x32_bf16 v[38:41], v[150:153], v[214:217], v[38:41]
	v_mfma_f32_16x16x32_bf16 v[30:33], v[130:133], v[222:225], v[30:33]
	v_mfma_f32_16x16x32_bf16 v[22:25], v[150:153], v[222:225], v[22:25]
	v_mfma_f32_16x16x32_bf16 v[14:17], v[130:133], v[230:233], v[14:17]
	v_mfma_f32_16x16x32_bf16 v[6:9], v[150:153], v[230:233], v[6:9]
	v_mfma_f32_16x16x32_bf16 v[58:61], v[158:161], v[206:209], v[58:61]
	v_mfma_f32_16x16x32_bf16 v[50:53], v[186:189], v[206:209], v[50:53]
	v_mfma_f32_16x16x32_bf16 v[42:45], v[158:161], v[214:217], v[42:45]
	v_mfma_f32_16x16x32_bf16 v[34:37], v[186:189], v[214:217], v[34:37]
	v_mfma_f32_16x16x32_bf16 v[26:29], v[158:161], v[222:225], v[26:29]
	v_mfma_f32_16x16x32_bf16 v[18:21], v[186:189], v[222:225], v[18:21]
	v_mfma_f32_16x16x32_bf16 v[10:13], v[158:161], v[230:233], v[10:13]
	v_mfma_f32_16x16x32_bf16 v[2:5], v[186:189], v[230:233], v[2:5]
	v_mfma_f32_16x16x32_bf16 v[62:65], v[146:149], v[210:213], v[62:65]
	v_mfma_f32_16x16x32_bf16 v[54:57], v[154:157], v[210:213], v[54:57]
	v_mfma_f32_16x16x32_bf16 v[46:49], v[146:149], v[218:221], v[46:49]
	v_mfma_f32_16x16x32_bf16 v[38:41], v[154:157], v[218:221], v[38:41]
	v_mfma_f32_16x16x32_bf16 v[30:33], v[146:149], v[226:229], v[30:33]
	v_mfma_f32_16x16x32_bf16 v[22:25], v[154:157], v[226:229], v[22:25]
	v_mfma_f32_16x16x32_bf16 v[14:17], v[146:149], v[234:237], v[14:17]
	v_mfma_f32_16x16x32_bf16 v[6:9], v[154:157], v[234:237], v[6:9]
	v_mfma_f32_16x16x32_bf16 v[58:61], v[178:181], v[210:213], v[58:61]
	v_mfma_f32_16x16x32_bf16 v[50:53], v[202:205], v[210:213], v[50:53]
	v_mfma_f32_16x16x32_bf16 v[42:45], v[178:181], v[218:221], v[42:45]
	v_mfma_f32_16x16x32_bf16 v[34:37], v[202:205], v[218:221], v[34:37]
	v_mfma_f32_16x16x32_bf16 v[26:29], v[178:181], v[226:229], v[26:29]
	v_mfma_f32_16x16x32_bf16 v[18:21], v[202:205], v[226:229], v[18:21]
	v_mfma_f32_16x16x32_bf16 v[10:13], v[178:181], v[234:237], v[10:13]
	v_mfma_f32_16x16x32_bf16 v[2:5], v[202:205], v[234:237], v[2:5]
	s_setprio 0
	s_barrier
	s_add_i32 s63, s63, 2
	s_add_u32 s2, s2, 0x100
	s_addc_u32 s3, s3, 0
	s_add_u32 s61, s61, 0x100
	s_addc_u32 s62, s62, 0
	s_cmp_gt_u32 s63, 13
	s_cbranch_scc0 .LBB0_1122
	s_branch .Lkexit_5

; #define PG8_BAR __builtin_amdgcn_s_barrier()
; template <class Epi, class Sched, bool ALIGN_EPI = false, bool SP2 = false>
; __device__ __forceinline__ void gemm_phase(PG8_LAS unsigned char* lds, const Gemm g, const Sched& S, const Epi& E) {
;     ...
;         if constexpr (ALIGN_EPI) { if (wr == 0) PG8_BAR; }
; DI void row_rstd(const float* ssq, int row0, int fq, float (&rs)[2][4]) {
; #pragma unroll
;     for (int ai = 0; ai < 2; ++ai)
; #pragma unroll
;         for (int m = 0; m < 4; ++m) {
;             const f32x4 v = *(const f32x4*)(ssq + (size_t)(row0 + ai * 128 + m * 16) * 16 + 4 * fq);
;             float s = (v[0] + v[1]) + (v[2] + v[3]);
;             s += __shfl_xor(s, 16); s += __shfl_xor(s, 32);
;             rs[ai][m] = rsqrtf(s * (1.0f / DM) + EPS);
;         }
; }
.Lkexit_5:
	v_lshl_add_u32 v234, s58, 8, v182
	v_ashrrev_i32_e32 v235, 31, v234
	v_add_u32_e32 v236, 0x80, v234
	v_ashrrev_i32_e32 v237, 31, v236
	v_lshlrev_b64 v[234:235], 6, v[234:235]
	v_lshlrev_b64 v[236:237], 6, v[236:237]
	v_lshl_add_u64 v[234:235], v[140:141], 0, v[234:235]
	v_lshl_add_u64 v[236:237], v[140:141], 0, v[236:237]
	global_load_dwordx4 v[202:205], v[234:235], off
	global_load_dwordx4 v[206:209], v[234:235], off offset:1024
	global_load_dwordx4 v[210:213], v[234:235], off offset:2048
	global_load_dwordx4 v[214:217], v[234:235], off offset:3072
	global_load_dwordx4 v[218:221], v[236:237], off
	global_load_dwordx4 v[222:225], v[236:237], off offset:1024
	global_load_dwordx4 v[226:229], v[236:237], off offset:2048
	global_load_dwordx4 v[230:233], v[236:237], off offset:3072
	s_and_b64 vcc, exec, s[44:45]
	s_cbranch_vccz .LBB0_1125
	s_barrier
